# PEER restructured: fp8 tables slice-major, U/V gathers swept per 128-dim slice in lockstep so each 2MB slice stays L2-resident
# speedup vs baseline: 1.1363x; 1.1163x over previous
.LBB0_975:
	s_waitcnt lgkmcnt(0)
	v_lshl_add_u64 v[14:15], s[20:21], 0, v[2:3]
	v_lshl_add_u64 v[16:17], s[10:11], 0, v[2:3]
	v_cmp_lt_u64_e32 vcc, s[4:5], v[6:7]
	v_mov_b32_e32 v10, 0
	v_mov_b32_e32 v11, 0
	v_cndmask_b32_e32 v27, v17, v15, vcc
	v_cndmask_b32_e32 v26, v16, v14, vcc
	global_load_dwordx4 v[14:17], v[26:27], off
	global_load_dwordx4 v[18:21], v[26:27], off offset:16
	global_load_dwordx4 v[22:25], v[26:27], off offset:32
	s_nop 0
	global_load_dwordx4 v[26:29], v[26:27], off offset:48
	v_cndmask_b32_e32 v38, v8, v9, vcc
	v_mov_b32_e32 v12, 0
	v_mov_b32_e32 v13, 0
	s_add_i32 s16, s3, 0xfffffbe1
	s_ashr_i32 s17, s16, 31
	s_lshl_b64 s[16:17], s[16:17], 12
	v_lshl_add_u64 v[32:33], s[16:17], 0, v[0:1]
	v_lshlrev_b64 v[34:35], 2, v[32:33]
	v_lshl_add_u64 v[36:37], s[20:21], 0, v[34:35]
	v_lshl_add_u64 v[34:35], s[22:23], 0, v[34:35]
	v_add_u32_e32 v40, s4, v0
	v_mov_b32_e32 v41, 0
	v_and_b32_e32 v42, 0x380, v40
	v_and_b32_e32 v43, 0xfffc00, v40
	v_lshlrev_b32_e32 v42, 14, v42
	v_lshrrev_b32_e32 v43, 3, v43
	v_and_b32_e32 v40, 0x100007f, v40
	v_or3_b32 v40, v40, v42, v43
	v_lshl_add_u64 v[30:31], s[90:91], 0, v[40:41]
	v_cmp_gt_u64_e32 vcc, s[14:15], v[32:33]
	v_lshl_add_u64 v[34:35], v[34:35], 0, s[8:9]
	s_add_i32 s16, s3, 0xfffffbe2
	v_cndmask_b32_e32 v35, v35, v37, vcc
	v_cndmask_b32_e32 v34, v34, v36, vcc
	v_cndmask_b32_e32 v39, v8, v9, vcc
	s_ashr_i32 s17, s16, 31
	s_lshl_b64 s[16:17], s[16:17], 12
	v_mov_b32_e32 v41, 0
	v_and_b32_e32 v42, 0x380, v32
	v_and_b32_e32 v43, 0xfffc00, v32
	v_lshlrev_b32_e32 v42, 14, v42
	v_lshrrev_b32_e32 v43, 3, v43
	v_and_b32_e32 v40, 0x100007f, v32
	v_or3_b32 v40, v40, v42, v43
	v_lshl_add_u64 v[32:33], s[90:91], 0, v[40:41]
	v_lshl_add_u64 v[2:3], v[2:3], 0, s[12:13]
	s_waitcnt vmcnt(3)
	v_mul_f32_e32 v14, v14, v38
	v_mul_f32_e32 v15, v15, v38
	s_waitcnt vmcnt(2)
	v_mul_f32_e32 v18, v38, v18
	v_mul_f32_e32 v19, v38, v19
	s_waitcnt vmcnt(1)
	v_mul_f32_e32 v22, v38, v22
	v_mul_f32_e32 v23, v38, v23
	s_waitcnt vmcnt(0)
	v_mul_f32_e32 v26, v38, v26
	v_mul_f32_e32 v27, v38, v27
	v_cvt_pk_fp8_f32 v10, v14, v15
	v_cvt_pk_fp8_f32 v11, v18, v19
	v_cvt_pk_fp8_f32 v12, v22, v23
	v_cvt_pk_fp8_f32 v13, v26, v27
	v_mul_f32_e32 v16, v16, v38
	v_mul_f32_e32 v17, v17, v38
	v_mul_f32_e32 v20, v38, v20
	v_mul_f32_e32 v21, v38, v21
	v_mul_f32_e32 v24, v38, v24
	v_mul_f32_e32 v25, v38, v25
	v_mul_f32_e32 v28, v38, v28
	v_mul_f32_e32 v29, v38, v29
	v_cvt_pk_fp8_f32 v10, v16, v17 op_sel:[0,0,1]
	v_cvt_pk_fp8_f32 v11, v20, v21 op_sel:[0,0,1]
	v_cvt_pk_fp8_f32 v12, v24, v25 op_sel:[0,0,1]
	v_cvt_pk_fp8_f32 v13, v28, v29 op_sel:[0,0,1]
	v_mov_b32_e32 v26, 0
	v_mov_b32_e32 v27, 0
	v_mov_b32_e32 v28, 0
	global_store_dwordx4 v[30:31], v[10:13], off
	global_load_dwordx4 v[10:13], v[34:35], off
	s_nop 0
	global_load_dwordx4 v[14:17], v[34:35], off offset:16
	global_load_dwordx4 v[18:21], v[34:35], off offset:32
	global_load_dwordx4 v[22:25], v[34:35], off offset:48
	v_mov_b32_e32 v29, 0
	v_lshl_add_u64 v[30:31], s[16:17], 0, v[0:1]
	v_lshlrev_b64 v[34:35], 2, v[30:31]
	v_lshl_add_u64 v[36:37], s[20:21], 0, v[34:35]
	v_lshl_add_u64 v[34:35], s[22:23], 0, v[34:35]
	v_cmp_gt_u64_e32 vcc, s[14:15], v[30:31]
	v_lshl_add_u64 v[34:35], v[34:35], 0, s[8:9]
	s_add_i32 s16, s3, 0xfffffbe3
	v_cndmask_b32_e32 v35, v35, v37, vcc
	v_cndmask_b32_e32 v34, v34, v36, vcc
	v_cndmask_b32_e32 v38, v8, v9, vcc
	s_ashr_i32 s17, s16, 31
	s_lshl_b64 s[16:17], s[16:17], 12
	v_mov_b32_e32 v41, 0
	v_and_b32_e32 v42, 0x380, v30
	v_and_b32_e32 v43, 0xfffc00, v30
	v_lshlrev_b32_e32 v42, 14, v42
	v_lshrrev_b32_e32 v43, 3, v43
	v_and_b32_e32 v40, 0x100007f, v30
	v_or3_b32 v40, v40, v42, v43
	v_lshl_add_u64 v[30:31], s[90:91], 0, v[40:41]
	s_add_i32 s3, s3, s0
	s_add_u32 s4, s4, s6
	s_addc_u32 s5, s5, s7
	s_cmpk_lt_i32 s3, 0x2420
	s_waitcnt vmcnt(3)
	v_mul_f32_e32 v10, v39, v10
	v_mul_f32_e32 v11, v39, v11
	s_waitcnt vmcnt(2)
	v_mul_f32_e32 v14, v39, v14
	v_mul_f32_e32 v15, v39, v15
	s_waitcnt vmcnt(1)
	v_mul_f32_e32 v18, v39, v18
	v_mul_f32_e32 v19, v39, v19
	s_waitcnt vmcnt(0)
	v_mul_f32_e32 v22, v39, v22
	v_mul_f32_e32 v23, v39, v23
	v_cvt_pk_fp8_f32 v26, v10, v11
	v_cvt_pk_fp8_f32 v27, v14, v15
	v_cvt_pk_fp8_f32 v28, v18, v19
	v_cvt_pk_fp8_f32 v29, v22, v23
	v_mul_f32_e32 v12, v39, v12
	v_mul_f32_e32 v13, v39, v13
	v_mul_f32_e32 v16, v39, v16
	v_mul_f32_e32 v17, v39, v17
	v_mul_f32_e32 v20, v39, v20
	v_mul_f32_e32 v21, v39, v21
	v_mul_f32_e32 v24, v39, v24
	v_mul_f32_e32 v25, v39, v25
	v_cvt_pk_fp8_f32 v26, v12, v13 op_sel:[0,0,1]
	v_cvt_pk_fp8_f32 v27, v16, v17 op_sel:[0,0,1]
	v_cvt_pk_fp8_f32 v28, v20, v21 op_sel:[0,0,1]
	v_cvt_pk_fp8_f32 v29, v24, v25 op_sel:[0,0,1]
	global_store_dwordx4 v[32:33], v[26:29], off
	global_load_dwordx4 v[10:13], v[34:35], off
	global_load_dwordx4 v[14:17], v[34:35], off offset:16
	global_load_dwordx4 v[18:21], v[34:35], off offset:32
	global_load_dwordx4 v[22:25], v[34:35], off offset:48
	v_mov_b32_e32 v26, 0
	v_mov_b32_e32 v27, 0
	v_mov_b32_e32 v28, 0
	v_mov_b32_e32 v29, 0
	v_lshl_add_u64 v[32:33], s[16:17], 0, v[0:1]
	v_lshlrev_b64 v[34:35], 2, v[32:33]
	v_lshl_add_u64 v[36:37], s[20:21], 0, v[34:35]
	v_lshl_add_u64 v[34:35], s[22:23], 0, v[34:35]
	v_cmp_gt_u64_e32 vcc, s[14:15], v[32:33]
	v_lshl_add_u64 v[34:35], v[34:35], 0, s[8:9]
	s_waitcnt vmcnt(3)
	v_mul_f32_e32 v10, v38, v10
	v_mul_f32_e32 v11, v38, v11
	s_waitcnt vmcnt(2)
	v_mul_f32_e32 v14, v38, v14
	v_mul_f32_e32 v15, v38, v15
	s_waitcnt vmcnt(1)
	v_mul_f32_e32 v18, v38, v18
	v_mul_f32_e32 v19, v38, v19
	s_waitcnt vmcnt(0)
	v_mul_f32_e32 v22, v38, v22
	v_mul_f32_e32 v23, v38, v23
	v_cvt_pk_fp8_f32 v26, v10, v11
	v_cvt_pk_fp8_f32 v27, v14, v15
	v_cvt_pk_fp8_f32 v28, v18, v19
	v_cvt_pk_fp8_f32 v29, v22, v23
	v_mul_f32_e32 v12, v38, v12
	v_mul_f32_e32 v13, v38, v13
	v_mul_f32_e32 v16, v38, v16
	v_mul_f32_e32 v17, v38, v17
	v_mul_f32_e32 v20, v38, v20
	v_mul_f32_e32 v21, v38, v21
	v_mul_f32_e32 v24, v38, v24
	v_mul_f32_e32 v25, v38, v25
	v_cvt_pk_fp8_f32 v26, v12, v13 op_sel:[0,0,1]
	v_cvt_pk_fp8_f32 v27, v16, v17 op_sel:[0,0,1]
	v_cvt_pk_fp8_f32 v28, v20, v21 op_sel:[0,0,1]
	v_cvt_pk_fp8_f32 v29, v24, v25 op_sel:[0,0,1]
	v_cndmask_b32_e32 v35, v35, v37, vcc
	v_cndmask_b32_e32 v34, v34, v36, vcc
	v_cndmask_b32_e32 v39, v8, v9, vcc
	global_store_dwordx4 v[30:31], v[26:29], off
	global_load_dwordx4 v[10:13], v[34:35], off
	global_load_dwordx4 v[14:17], v[34:35], off offset:16
	global_load_dwordx4 v[18:21], v[34:35], off offset:32
	global_load_dwordx4 v[22:25], v[34:35], off offset:48
	v_mov_b32_e32 v26, 0
	v_mov_b32_e32 v27, 0
	v_mov_b32_e32 v28, 0
	v_mov_b32_e32 v29, 0
	s_waitcnt vmcnt(3)
	v_mul_f32_e32 v10, v39, v10
	v_mul_f32_e32 v11, v39, v11
	s_waitcnt vmcnt(2)
	v_mul_f32_e32 v14, v39, v14
	v_mul_f32_e32 v15, v39, v15
	s_waitcnt vmcnt(1)
	v_mul_f32_e32 v18, v39, v18
	v_mul_f32_e32 v19, v39, v19
	s_waitcnt vmcnt(0)
	v_mul_f32_e32 v22, v39, v22
	v_mul_f32_e32 v23, v39, v23
	v_cvt_pk_fp8_f32 v26, v10, v11
	v_cvt_pk_fp8_f32 v27, v14, v15
	v_cvt_pk_fp8_f32 v28, v18, v19
	v_cvt_pk_fp8_f32 v29, v22, v23
	v_mul_f32_e32 v12, v39, v12
	v_mul_f32_e32 v13, v39, v13
	v_mul_f32_e32 v16, v39, v16
	v_mul_f32_e32 v17, v39, v17
	v_mul_f32_e32 v20, v39, v20
	v_mul_f32_e32 v21, v39, v21
	v_mul_f32_e32 v24, v39, v24
	v_mul_f32_e32 v25, v39, v25
	v_cvt_pk_fp8_f32 v26, v12, v13 op_sel:[0,0,1]
	v_cvt_pk_fp8_f32 v27, v16, v17 op_sel:[0,0,1]
	v_cvt_pk_fp8_f32 v28, v20, v21 op_sel:[0,0,1]
	v_cvt_pk_fp8_f32 v29, v24, v25 op_sel:[0,0,1]
	v_mov_b32_e32 v41, 0
	v_and_b32_e32 v42, 0x380, v32
	v_and_b32_e32 v43, 0xfffc00, v32
	v_lshlrev_b32_e32 v42, 14, v42
	v_lshrrev_b32_e32 v43, 3, v43
	v_and_b32_e32 v40, 0x100007f, v32
	v_or3_b32 v40, v40, v42, v43
	v_lshl_add_u64 v[10:11], s[90:91], 0, v[40:41]
	global_store_dwordx4 v[10:11], v[26:29], off
	s_cbranch_scc1 .LBB0_975

.LBB0_1113:
	s_cmp_lt_i32 s92, 10
	s_cselect_b64 s[0:1], -1, 0
	s_cmp_gt_i32 s93, 9
	s_cselect_b64 s[4:5], -1, 0
	s_and_b64 s[0:1], s[0:1], s[4:5]
	s_andn2_b64 vcc, exec, s[0:1]
	s_cbranch_vccnz .LBB0_1592
	v_lshl_add_u32 v96, s2, 2, v214
	s_movk_i32 s0, 0x4200
	v_cmp_gt_i32_e32 vcc, s0, v96
	s_and_saveexec_b64 s[28:29], vcc
	s_cbranch_execz .LBB0_1538
	s_waitcnt vmcnt(25)
	v_mbcnt_lo_u32_b32 v6, -1, 0
	v_mbcnt_hi_u32_b32 v6, -1, v6
	v_and_b32_e32 v7, 64, v6
	v_add_u32_e32 v7, 64, v7
	v_xor_b32_e32 v8, 32, v6
	v_cmp_lt_i32_e64 s[0:1], v8, v7
	v_and_b32_e32 v4, 63, v218
	v_add_u32_e32 v0, -16, v4
	v_cndmask_b32_e64 v8, v6, v8, s[0:1]
	v_lshlrev_b32_e32 v137, 2, v8
	v_xor_b32_e32 v8, 16, v6
	v_cmp_lt_i32_e64 s[0:1], v8, v7
	v_min_u32_e32 v0, v0, v4
	v_subrev_co_u32_e32 v1, vcc, 24, v4
	v_cndmask_b32_e64 v8, v6, v8, s[0:1]
	v_lshlrev_b32_e32 v138, 2, v8
	v_xor_b32_e32 v8, 8, v6
	v_cmp_lt_i32_e64 s[0:1], v8, v7
	v_cndmask_b32_e32 v0, v1, v0, vcc
	v_subrev_co_u32_e64 v1, s[18:19], 29, v4
	v_cndmask_b32_e64 v8, v6, v8, s[0:1]
	v_lshlrev_b32_e32 v139, 2, v8
	v_xor_b32_e32 v8, 4, v6
	v_cmp_lt_i32_e64 s[0:1], v8, v7
	v_mul_u32_u24_e32 v136, 0x500, v214
	v_cndmask_b32_e64 v0, v1, v0, s[18:19]
	v_cndmask_b32_e64 v8, v6, v8, s[0:1]
	v_lshlrev_b32_e32 v140, 2, v8
	v_xor_b32_e32 v8, 2, v6
	v_cmp_lt_i32_e64 s[0:1], v8, v7
	v_subrev_co_u32_e64 v1, s[20:21], 33, v4
	s_nop 0
	v_cndmask_b32_e64 v8, v6, v8, s[0:1]
	v_lshlrev_b32_e32 v141, 2, v8
	v_xor_b32_e32 v8, 1, v6
	v_cmp_lt_i32_e64 s[0:1], v8, v7
	v_and_b32_e32 v7, 58, v218
	v_cndmask_b32_e64 v0, v1, v0, s[20:21]
	v_cndmask_b32_e64 v6, v6, v8, s[0:1]
	v_cmp_ne_u32_e64 s[0:1], 0, v4
	v_lshlrev_b32_e32 v142, 2, v6
	v_and_b32_e32 v6, 1, v218
	v_cndmask_b32_e64 v144, 0, 1, s[0:1]
	v_cmp_lt_u32_e64 s[0:1], 1, v4
	v_cmp_eq_u32_e64 s[6:7], 0, v6
	v_and_b32_e32 v6, 2, v218
	v_cndmask_b32_e64 v145, 0, 1, s[0:1]
	v_cmp_lt_u32_e64 s[0:1], 2, v4
	v_lshlrev_b32_e32 v8, 4, v218
	v_subrev_co_u32_e64 v1, s[22:23], 36, v4
	v_cndmask_b32_e64 v146, 0, 1, s[0:1]
	v_cmp_lt_u32_e64 s[0:1], 3, v4
	v_cmp_eq_u32_e64 s[8:9], 0, v6
	v_and_b32_e32 v6, 4, v218
	v_cndmask_b32_e64 v147, 0, 1, s[0:1]
	v_cmp_lt_u32_e64 s[0:1], 4, v4
	v_and_or_b32 v8, v8, 16, v136
	v_lshlrev_b32_e32 v7, 2, v7
	v_cndmask_b32_e64 v148, 0, 1, s[0:1]
	v_cmp_lt_u32_e64 s[0:1], 5, v4
	v_cndmask_b32_e64 v0, v1, v0, s[22:23]
	v_subrev_co_u32_e64 v1, s[26:27], 38, v4
	v_cndmask_b32_e64 v149, 0, 1, s[0:1]
	v_cmp_lt_u32_e64 s[0:1], 6, v4
	v_cmp_eq_u32_e64 s[10:11], 0, v6
	v_or3_b32 v195, v8, v7, v6
	v_cndmask_b32_e64 v150, 0, 1, s[0:1]
	v_cmp_lt_u32_e64 s[0:1], 7, v4
	v_cndmask_b32_e64 v2, v1, v0, s[26:27]
	v_subrev_co_u32_e64 v3, s[24:25], 40, v4
	v_cndmask_b32_e64 v151, 0, 1, s[0:1]
	v_cmp_lt_u32_e64 s[0:1], 8, v4
	v_subrev_u32_e32 v0, 34, v4
	v_cmp_gt_u32_e64 s[4:5], 50, v4
	v_cndmask_b32_e64 v152, 0, 1, s[0:1]
	v_cmp_lt_u32_e64 s[0:1], 9, v4
	v_readlane_b32 s36, v242, 25
	v_cndmask_b32_e64 v5, 0, v0, s[4:5]
	v_cndmask_b32_e64 v153, 0, 1, s[0:1]
	v_cmp_lt_u32_e64 s[0:1], 10, v4
	v_lshlrev_b32_e32 v0, 4, v4
	v_mov_b32_e32 v1, 0
	v_cndmask_b32_e64 v154, 0, 1, s[0:1]
	v_cmp_lt_u32_e64 s[0:1], 11, v4
	v_readlane_b32 s38, v242, 27
	v_readlane_b32 s39, v242, 28
	v_cndmask_b32_e64 v155, 0, 1, s[0:1]
	v_cmp_lt_u32_e64 s[0:1], 12, v4
	v_lshl_add_u64 v[106:107], s[38:39], 0, v[0:1]
	v_lshlrev_b32_e32 v0, 5, v4
	v_cndmask_b32_e64 v156, 0, 1, s[0:1]
	v_cmp_lt_u32_e64 s[0:1], 13, v4
	v_mov_b32_e32 v101, v1
	v_mov_b32_e32 v99, v1
	v_cndmask_b32_e64 v157, 0, 1, s[0:1]
	v_cmp_lt_u32_e64 s[0:1], 14, v4
	v_lshl_add_u64 v[110:111], s[82:83], 0, v[0:1]
	v_readlane_b32 s64, v242, 1
	v_cndmask_b32_e64 v158, 0, 1, s[0:1]
	v_cmp_lt_u32_e64 s[0:1], 15, v4
	v_readlane_b32 s65, v242, 2
	v_readlane_b32 s66, v242, 3
	v_cndmask_b32_e64 v159, 0, 1, s[0:1]
	v_cmp_lt_u32_e64 s[0:1], 16, v4
	v_cndmask_b32_e32 v6, 2, v159, vcc
	v_cndmask_b32_e64 v6, 3, v6, s[18:19]
	v_cndmask_b32_e64 v160, 0, 1, s[0:1]
	v_cmp_lt_u32_e64 s[0:1], 17, v4
	v_cmp_gt_u32_e32 vcc, 42, v4
	v_cndmask_b32_e64 v6, 4, v6, s[20:21]
	v_cndmask_b32_e64 v161, 0, 1, s[0:1]
	v_cmp_lt_u32_e64 s[0:1], 18, v4
	v_cndmask_b32_e32 v3, 0, v3, vcc
	v_cndmask_b32_e64 v6, 5, v6, s[22:23]
	s_waitcnt vmcnt(18)
	v_cndmask_b32_e64 v162, 0, 1, s[0:1]
	v_cmp_lt_u32_e64 s[0:1], 19, v4
	v_cndmask_b32_e64 v98, v3, v2, s[24:25]
	v_cndmask_b32_e64 v6, 6, v6, s[26:27]
	v_cndmask_b32_e64 v163, 0, 1, s[0:1]
	v_cmp_lt_u32_e64 s[0:1], 20, v4
	v_cndmask_b32_e64 v5, v5, 7, vcc
	v_mov_b32_e32 v3, v1
	v_cndmask_b32_e64 v164, 0, 1, s[0:1]
	v_cmp_lt_u32_e64 s[0:1], 21, v4
	v_ashrrev_i32_e32 v1, 31, v98
	v_mov_b32_e32 v0, v98
	v_cndmask_b32_e64 v165, 0, 1, s[0:1]
	v_cmp_lt_u32_e64 s[0:1], 22, v4
	v_cndmask_b32_e64 v100, v5, v6, s[24:25]
	v_lshl_add_u64 v[0:1], v[0:1], 2, s[84:85]
	s_waitcnt vmcnt(6)
	v_cndmask_b32_e64 v166, 0, 1, s[0:1]
	v_cmp_lt_u32_e64 s[0:1], 23, v4
	v_lshlrev_b32_e32 v2, 6, v4
	v_readlane_b32 s67, v242, 4
	v_cndmask_b32_e64 v167, 0, 1, s[0:1]
	v_cmp_lt_u32_e64 s[0:1], 24, v4
	v_readlane_b32 s68, v242, 5
	v_readlane_b32 s69, v242, 6
	v_cndmask_b32_e64 v168, 0, 1, s[0:1]
	v_cmp_lt_u32_e64 s[0:1], 25, v4
	v_readlane_b32 s70, v242, 7
	v_readlane_b32 s71, v242, 8
	v_cndmask_b32_e64 v169, 0, 1, s[0:1]
	v_cmp_lt_u32_e64 s[0:1], 26, v4
	v_readlane_b32 s72, v242, 9
	v_readlane_b32 s73, v242, 10
	v_cndmask_b32_e64 v170, 0, 1, s[0:1]
	v_cmp_lt_u32_e64 s[0:1], 27, v4
	v_readlane_b32 s74, v242, 11
	v_readlane_b32 s75, v242, 12
	v_cndmask_b32_e64 v171, 0, 1, s[0:1]
	v_cmp_lt_u32_e64 s[0:1], 28, v4
	v_readlane_b32 s76, v242, 13
	v_readlane_b32 s77, v242, 14
	v_cndmask_b32_e64 v172, 0, 1, s[0:1]
	v_cmp_lt_u32_e64 s[0:1], 29, v4
	v_readlane_b32 s78, v242, 15
	v_readlane_b32 s79, v242, 16
	v_cndmask_b32_e64 v173, 0, 1, s[0:1]
	v_cmp_lt_u32_e64 s[0:1], 30, v4
	v_lshl_add_u64 v[102:103], s[64:65], 0, v[2:3]
	v_readlane_b32 s64, v243, 33
	v_cndmask_b32_e64 v174, 0, 1, s[0:1]
	v_cmp_lt_u32_e64 s[0:1], 31, v4
	s_movk_i32 s30, 0x500
	v_bfe_u32 v194, v218, 3, 3
	v_cndmask_b32_e64 v175, 0, 1, s[0:1]
	v_cmp_lt_u32_e64 s[0:1], 32, v4
	v_readlane_b32 s42, v242, 31
	v_readlane_b32 s65, v243, 34
	v_cndmask_b32_e64 v176, 0, 1, s[0:1]
	v_cmp_lt_u32_e64 s[0:1], 33, v4
	v_readlane_b32 s66, v243, 35
	v_readlane_b32 s67, v243, 36
	v_cndmask_b32_e64 v177, 0, 1, s[0:1]
	v_cmp_lt_u32_e64 s[0:1], 34, v4
	v_readlane_b32 s68, v243, 37
	v_readlane_b32 s78, v243, 47
	v_cndmask_b32_e64 v178, 0, 1, s[0:1]
	v_cmp_lt_u32_e64 s[0:1], 35, v4
	v_readlane_b32 s79, v243, 48
	v_lshl_or_b32 v143, v4, 2, v136
	v_cndmask_b32_e64 v179, 0, 1, s[0:1]
	v_cmp_lt_u32_e64 s[0:1], 36, v4
	v_cmp_eq_u32_e64 s[12:13], 6, v194
	v_cmp_eq_u32_e64 s[14:15], 7, v194
	v_cndmask_b32_e64 v180, 0, 1, s[0:1]
	v_cmp_lt_u32_e64 s[0:1], 37, v4
	v_cmp_eq_u32_e64 s[16:17], 0, v4
	s_lshl_b32 s3, s42, 2
	v_cndmask_b32_e64 v181, 0, 1, s[0:1]
	v_cmp_lt_u32_e64 s[0:1], 38, v4
	v_lshl_add_u64 v[104:105], s[78:79], 0, v[2:3]
	s_mov_b64 s[18:19], 0
	v_cndmask_b32_e64 v182, 0, 1, s[0:1]
	v_cmp_lt_u32_e64 s[0:1], 39, v4
	v_mov_b32_e32 v197, 0xff61b1e6
	s_movk_i32 s31, 0x3f80
	v_cndmask_b32_e64 v183, 0, 1, s[0:1]
	v_cmp_lt_u32_e64 s[0:1], 40, v4
	s_mov_b64 s[20:21], 0x80
	s_waitcnt vmcnt(4)
	v_mov_b32_e32 v198, 0x358637bd
	v_cndmask_b32_e64 v184, 0, 1, s[0:1]
	v_cmp_lt_u32_e64 s[0:1], 41, v4
	s_mov_b32 s35, 0x800000
	s_mov_b32 s54, 0x378e98ab
	v_cndmask_b32_e64 v185, 0, 1, s[0:1]
	v_cmp_lt_u32_e64 s[0:1], 42, v4
	s_mov_b32 s55, 0x3b7cd369
	s_mov_b32 s56, 0xbcc618b2
	v_cndmask_b32_e64 v186, 0, 1, s[0:1]
	v_cmp_lt_u32_e64 s[0:1], 43, v4
	s_mov_b32 s57, 0x3dda74e4
	s_mov_b32 s62, 0x3f228afd
	v_cndmask_b32_e64 v187, 0, 1, s[0:1]
	v_cmp_lt_u32_e64 s[0:1], 44, v4
	s_mov_b32 s63, 0x3e03c728
	s_mov_b32 s64, 0xbfb8aa3b
	v_cndmask_b32_e64 v188, 0, 1, s[0:1]
	v_cmp_lt_u32_e64 s[0:1], 45, v4
	s_mov_b32 s65, 0x42ce8ed0
	s_mov_b32 s66, 0xc2b17218
	v_cndmask_b32_e64 v189, 0, 1, s[0:1]
	v_cmp_lt_u32_e64 s[0:1], 46, v4
	v_mov_b32_e32 v199, 0x3ba10414
	s_brev_b32 s67, -2
	v_cndmask_b32_e64 v190, 0, 1, s[0:1]
	v_cmp_lt_u32_e64 s[0:1], 47, v4
	s_movk_i32 s68, 0x41ff
	v_mov_b32_e32 v200, 0xb9c68948
	v_cndmask_b32_e64 v191, 0, 1, s[0:1]
	v_cmp_lt_u32_e64 s[0:1], 48, v4
	v_mov_b32_e32 v201, 0x7f800000
	v_readlane_b32 s37, v242, 26
	v_cndmask_b32_e64 v192, 0, 1, s[0:1]
	v_cmp_lt_u32_e64 s[0:1], 49, v4
	v_readlane_b32 s40, v242, 29
	v_readlane_b32 s41, v242, 30
	v_cndmask_b32_e64 v193, 0, 1, s[0:1]
	s_mov_b64 s[0:1], 0x1000000
	v_lshl_add_u64 v[108:109], v[106:107], 0, s[0:1]
	s_mov_b64 s[0:1], 0xc0
	v_lshl_add_u64 v[112:113], v[0:1], 0, s[0:1]
	v_add_u32_e32 v0, 32, v100
	v_ashrrev_i32_e32 v1, 31, v0
	v_lshl_add_u64 v[114:115], v[0:1], 2, s[84:85]
	v_mov_b32_e32 v0, 0x120
	v_mad_u32_u24 v196, v214, s30, v0
	v_readlane_b32 s43, v242, 32
	v_readlane_b32 s69, v243, 38
	v_readlane_b32 s70, v243, 39
	v_readlane_b32 s71, v243, 40
	v_readlane_b32 s72, v243, 41
	v_readlane_b32 s73, v243, 42
	v_readlane_b32 s74, v243, 43
	v_readlane_b32 s75, v243, 44
	v_readlane_b32 s76, v243, 45
	v_readlane_b32 s77, v243, 46
	s_mov_b32 s26, 0
	v_and_b32_e32 v202, 63, v218
	v_mul_u32_u24_e32 v204, 0x3640, v214
	v_lshlrev_b32_e32 v202, 2, v202
	v_add_u32_e32 v204, 0x1400, v204
	v_add_u32_e32 v202, v202, v204
	v_add_u32_e32 v204, 0x3600, v204
	v_mov_b32_e32 v203, 0
	s_branch .LBB0_1117

.LBB0_1524:
	s_or_b64 exec, exec, s[0:1]
	s_branch .Lpf_b_rejoin
.LBB0_1117:
	v_ashrrev_i32_e32 v97, 31, v96
	v_lshlrev_b64 v[0:1], 12, v[96:97]
	v_lshl_add_u64 v[116:117], v[102:103], 0, v[0:1]
	s_waitcnt lgkmcnt(0)
	global_load_dwordx4 v[12:15], v[116:117], off
	global_load_dwordx4 v[8:11], v[116:117], off offset:16
	global_load_dwordx4 v[4:7], v[116:117], off offset:32
	global_load_dwordx4 v[0:3], v[116:117], off offset:48
	global_load_dwordx4 v[16:19], v[104:105], off offset:48
	global_load_dwordx4 v[20:23], v[104:105], off offset:32
	global_load_dwordx4 v[24:27], v[104:105], off offset:16
	global_load_dwordx4 v[28:31], v[104:105], off
	v_lshlrev_b64 v[118:119], 10, v[96:97]
	v_lshl_add_u64 v[32:33], s[84:85], 0, v[118:119]
	v_lshl_add_u64 v[34:35], v[100:101], 2, v[32:33]
	v_lshl_add_u64 v[32:33], v[98:99], 2, v[32:33]
	global_load_dword v42, v[34:35], off
	global_load_dword v43, v[32:33], off offset:64
	s_mov_b32 s24, 0
	s_waitcnt vmcnt(9)
	v_pk_mul_f32 v[32:33], v[12:13], v[12:13]
	v_pk_mul_f32 v[34:35], v[14:15], v[14:15]
	v_add_f32_e32 v32, v32, v33
	v_add_f32_e32 v32, v32, v34
	s_waitcnt vmcnt(8)
	v_pk_mul_f32 v[36:37], v[8:9], v[8:9]
	v_add_f32_e32 v32, v32, v35
	v_add_f32_e32 v32, v32, v36
	v_pk_mul_f32 v[38:39], v[10:11], v[10:11]
	v_add_f32_e32 v32, v32, v37
	v_add_f32_e32 v32, v32, v38
	s_waitcnt vmcnt(7)
	v_pk_mul_f32 v[40:41], v[4:5], v[4:5]
	v_add_f32_e32 v32, v32, v39
	v_add_f32_e32 v32, v32, v40
	v_pk_mul_f32 v[44:45], v[6:7], v[6:7]
	v_add_f32_e32 v32, v32, v41
	v_add_f32_e32 v32, v32, v44
	s_waitcnt vmcnt(6)
	v_pk_mul_f32 v[46:47], v[0:1], v[0:1]
	v_add_f32_e32 v32, v32, v45
	v_add_f32_e32 v32, v32, v46
	v_pk_mul_f32 v[48:49], v[2:3], v[2:3]
	v_add_f32_e32 v32, v32, v47
	v_add_f32_e32 v32, v32, v48
	v_add_f32_e32 v32, v32, v49
	ds_bpermute_b32 v33, v137, v32
	v_lshl_add_u64 v[36:37], v[112:113], 0, v[118:119]
	v_lshl_add_u64 v[38:39], v[114:115], 0, v[118:119]
	s_waitcnt lgkmcnt(0)
	v_add_f32_e32 v32, v32, v33
	ds_bpermute_b32 v33, v138, v32
	s_waitcnt lgkmcnt(0)
	v_add_f32_e32 v32, v32, v33
	ds_bpermute_b32 v33, v139, v32
	s_waitcnt lgkmcnt(0)
	v_add_f32_e32 v32, v32, v33
	ds_bpermute_b32 v33, v140, v32
	s_waitcnt lgkmcnt(0)
	v_add_f32_e32 v32, v32, v33
	ds_bpermute_b32 v33, v141, v32
	s_waitcnt lgkmcnt(0)
	v_add_f32_e32 v72, v32, v33
	ds_bpermute_b32 v73, v142, v72

.Lpf_b_rejoin:
	s_waitcnt lgkmcnt(0)
	v_add_f32_e32 v72, v72, v73
	v_fmamk_f32 v72, v72, 0x3a800000, v198
	v_mul_f32_e32 v73, 0x4b800000, v72
	v_cmp_gt_f32_e32 vcc, s35, v72
	s_nop 1
	v_cndmask_b32_e32 v72, v72, v73, vcc
	v_rsq_f32_e32 v72, v72
	s_nop 0
	v_mul_f32_e32 v73, 0x45800000, v72
	v_cndmask_b32_e32 v72, v72, v73, vcc
	v_mul_f32_e32 v72, 0x3b800000, v72
	v_add_u32_e32 v32, 0x100, v143
	ds_read2st64_b32 v[34:35], v32 offset1:1
	ds_read2st64_b32 v[36:37], v32 offset0:2 offset1:3
	s_lshl_b32 s0, s26, 9
	v_add_u32_e32 v33, s0, v202
	s_lshl_b32 s0, s26, 2
	v_add_u32_e32 v38, s0, v204
	s_waitcnt lgkmcnt(0)
	v_lshlrev_b32_e32 v34, 7, v34
	v_lshlrev_b32_e32 v35, 7, v35
	ds_write2st64_b32 v33, v34, v35 offset1:1
	ds_write2st64_b32 v33, v36, v37 offset0:18 offset1:19
	ds_write2st64_b32 v33, v203, v203 offset0:36 offset1:37
	ds_write_b32 v38, v72
	s_add_i32 s26, s26, 1
	v_add_u32_e32 v96, s3, v96
	s_nop 0
	v_readfirstlane_b32 s0, v96
	s_cmpk_lt_i32 s0, 0x4200
	s_cbranch_scc1 .LBB0_1117
	s_waitcnt lgkmcnt(0)
	v_readlane_b32 s4, v242, 1
	v_readlane_b32 s5, v242, 2
	v_readlane_b32 s6, v243, 47
	v_readlane_b32 s7, v243, 48
	v_readlane_b32 s8, v242, 27
	v_readlane_b32 s9, v242, 28
	v_readlane_b32 s12, v242, 19
	v_readlane_b32 s13, v242, 20
	v_readlane_b32 s14, v243, 6
	v_readlane_b32 s15, v243, 7
	v_readfirstlane_b32 s27, v214
	s_add_u32 s10, s8, 0x1000000
	s_addc_u32 s11, s9, 0
	s_lshl_b32 s0, s2, 2
	s_add_i32 s27, s27, s0
	v_and_b32_e32 v188, 7, v218
	v_bfe_u32 v190, v218, 3, 3
	v_lshlrev_b32_e32 v189, 6, v188
	v_lshlrev_b32_e32 v213, 5, v188
	v_lshlrev_b32_e32 v188, 4, v188
	v_lshl_add_u32 v211, v190, 3, v189
	v_lshl_add_u32 v213, v190, 2, v213
	v_bfe_u32 v209, v218, 2, 1
	v_lshlrev_b32_e32 v190, 6, v190
	v_lshlrev_b32_e32 v209, 5, v209
	v_add_u32_e32 v190, v190, v204
	v_add_u32_e32 v190, 0xffffca00, v190
	v_add_u32_e32 v209, v209, v190
	v_add_u32_e32 v209, 0x2400, v209
	s_mov_b32 s38, 0xffff0000
	s_mov_b32 s39, 0xffff0000
	s_mov_b32 s16, 0
.Lpb_slice:
	s_mov_b32 s17, 0
.Lpb_unit:
	s_lshl_b32 s0, s17, 11
	s_add_i32 s0, s0, s27
	s_lshl_b32 s1, s16, 9
	s_lshl_b32 s24, s0, 12
	s_add_u32 s24, s24, s1
	s_add_u32 s20, s4, s24
	s_addc_u32 s21, s5, 0
	s_add_u32 s36, s6, s1
	s_addc_u32 s37, s7, 0
	s_lshl_b32 s25, s16, 21
	s_add_u32 s18, s8, s25
	s_addc_u32 s19, s9, 0
	s_lshl_b32 s25, s17, 9
	v_add_u32_e32 v205, s25, v190
	v_add_u32_e32 v210, s25, v209
	s_lshl_b32 s25, s17, 2
	v_add_u32_e32 v206, s25, v204
	ds_read_b128 v[64:67], v205
	ds_read_b128 v[68:71], v205 offset:16
	ds_read_b128 v[72:75], v205 offset:32
	ds_read_b128 v[76:79], v205 offset:48
	ds_read_b32 v208, v206
	global_load_dwordx4 v[80:83], v189, s[20:21]
	global_load_dwordx4 v[84:87], v189, s[20:21] offset:16
	global_load_dwordx4 v[88:91], v189, s[20:21] offset:32
	global_load_dwordx4 v[92:95], v189, s[20:21] offset:48
	global_load_dwordx4 v[96:99], v189, s[36:37]
	global_load_dwordx4 v[100:103], v189, s[36:37] offset:16
	global_load_dwordx4 v[104:107], v189, s[36:37] offset:32
	global_load_dwordx4 v[108:111], v189, s[36:37] offset:48
	s_waitcnt lgkmcnt(1)
	v_add_u32_e32 v64, v64, v188
	v_add_u32_e32 v65, v65, v188
	v_add_u32_e32 v66, v66, v188
	v_add_u32_e32 v67, v67, v188
	v_add_u32_e32 v68, v68, v188
	v_add_u32_e32 v69, v69, v188
	v_add_u32_e32 v70, v70, v188
	v_add_u32_e32 v71, v71, v188
	v_add_u32_e32 v72, v72, v188
	v_add_u32_e32 v73, v73, v188
	v_add_u32_e32 v74, v74, v188
	v_add_u32_e32 v75, v75, v188
	v_add_u32_e32 v76, v76, v188
	v_add_u32_e32 v77, v77, v188
	v_add_u32_e32 v78, v78, v188
	v_add_u32_e32 v79, v79, v188
	global_load_dwordx4 v[0:3], v64, s[18:19]
	global_load_dwordx4 v[4:7], v65, s[18:19]
	global_load_dwordx4 v[8:11], v66, s[18:19]
	global_load_dwordx4 v[12:15], v67, s[18:19]
	global_load_dwordx4 v[16:19], v68, s[18:19]
	global_load_dwordx4 v[20:23], v69, s[18:19]
	global_load_dwordx4 v[24:27], v70, s[18:19]
	global_load_dwordx4 v[28:31], v71, s[18:19]
	global_load_dwordx4 v[32:35], v72, s[18:19]
	global_load_dwordx4 v[36:39], v73, s[18:19]
	global_load_dwordx4 v[40:43], v74, s[18:19]
	global_load_dwordx4 v[44:47], v75, s[18:19]
	global_load_dwordx4 v[48:51], v76, s[18:19]
	global_load_dwordx4 v[52:55], v77, s[18:19]
	global_load_dwordx4 v[56:59], v78, s[18:19]
	global_load_dwordx4 v[60:63], v79, s[18:19]
	s_waitcnt vmcnt(16) lgkmcnt(0)
	v_pk_mul_f32 v[96:97], v[96:97], v[208:209] op_sel_hi:[1,0]
	v_pk_mul_f32 v[98:99], v[98:99], v[208:209] op_sel_hi:[1,0]
	v_pk_mul_f32 v[100:101], v[100:101], v[208:209] op_sel_hi:[1,0]
	v_pk_mul_f32 v[102:103], v[102:103], v[208:209] op_sel_hi:[1,0]
	v_pk_mul_f32 v[104:105], v[104:105], v[208:209] op_sel_hi:[1,0]
	v_pk_mul_f32 v[106:107], v[106:107], v[208:209] op_sel_hi:[1,0]
	v_pk_mul_f32 v[108:109], v[108:109], v[208:209] op_sel_hi:[1,0]
	v_pk_mul_f32 v[110:111], v[110:111], v[208:209] op_sel_hi:[1,0]
	v_pk_mul_f32 v[80:81], v[80:81], v[96:97]
	v_pk_mul_f32 v[82:83], v[82:83], v[98:99]
	v_pk_mul_f32 v[84:85], v[84:85], v[100:101]
	v_pk_mul_f32 v[86:87], v[86:87], v[102:103]
	v_pk_mul_f32 v[88:89], v[88:89], v[104:105]
	v_pk_mul_f32 v[90:91], v[90:91], v[106:107]
	v_pk_mul_f32 v[92:93], v[92:93], v[108:109]
	v_pk_mul_f32 v[94:95], v[94:95], v[110:111]
	s_waitcnt vmcnt(15)
	v_cvt_pk_f32_fp8_e32 v[168:169], v0
	v_cvt_pk_f32_fp8_sdwa v[170:171], v0 src0_sel:WORD_1
	v_cvt_pk_f32_fp8_e32 v[172:173], v1
	v_cvt_pk_f32_fp8_sdwa v[174:175], v1 src0_sel:WORD_1
	v_cvt_pk_f32_fp8_e32 v[176:177], v2
	v_cvt_pk_f32_fp8_sdwa v[178:179], v2 src0_sel:WORD_1
	v_cvt_pk_f32_fp8_e32 v[180:181], v3
	v_cvt_pk_f32_fp8_sdwa v[182:183], v3 src0_sel:WORD_1
	v_pk_mul_f32 v[184:185], v[168:169], v[80:81]
	v_pk_mul_f32 v[186:187], v[170:171], v[82:83]
	v_pk_fma_f32 v[184:185], v[172:173], v[84:85], v[184:185]
	v_pk_fma_f32 v[186:187], v[174:175], v[86:87], v[186:187]
	v_pk_fma_f32 v[184:185], v[176:177], v[88:89], v[184:185]
	v_pk_fma_f32 v[186:187], v[178:179], v[90:91], v[186:187]
	v_pk_fma_f32 v[184:185], v[180:181], v[92:93], v[184:185]
	v_pk_fma_f32 v[186:187], v[182:183], v[94:95], v[186:187]
	v_pk_add_f32 v[184:185], v[184:185], v[186:187]
	v_add_f32_e32 v112, v184, v185
	s_waitcnt vmcnt(14)
	v_cvt_pk_f32_fp8_e32 v[168:169], v4
	v_cvt_pk_f32_fp8_sdwa v[170:171], v4 src0_sel:WORD_1
	v_cvt_pk_f32_fp8_e32 v[172:173], v5
	v_cvt_pk_f32_fp8_sdwa v[174:175], v5 src0_sel:WORD_1
	v_cvt_pk_f32_fp8_e32 v[176:177], v6
	v_cvt_pk_f32_fp8_sdwa v[178:179], v6 src0_sel:WORD_1
	v_cvt_pk_f32_fp8_e32 v[180:181], v7
	v_cvt_pk_f32_fp8_sdwa v[182:183], v7 src0_sel:WORD_1
	v_pk_mul_f32 v[184:185], v[168:169], v[80:81]
	v_pk_mul_f32 v[186:187], v[170:171], v[82:83]
	v_pk_fma_f32 v[184:185], v[172:173], v[84:85], v[184:185]
	v_pk_fma_f32 v[186:187], v[174:175], v[86:87], v[186:187]
	v_pk_fma_f32 v[184:185], v[176:177], v[88:89], v[184:185]
	v_pk_fma_f32 v[186:187], v[178:179], v[90:91], v[186:187]
	v_pk_fma_f32 v[184:185], v[180:181], v[92:93], v[184:185]
	v_pk_fma_f32 v[186:187], v[182:183], v[94:95], v[186:187]
	v_pk_add_f32 v[184:185], v[184:185], v[186:187]
	v_add_f32_e32 v113, v184, v185
	s_waitcnt vmcnt(13)
	v_cvt_pk_f32_fp8_e32 v[168:169], v8
	v_cvt_pk_f32_fp8_sdwa v[170:171], v8 src0_sel:WORD_1
	v_cvt_pk_f32_fp8_e32 v[172:173], v9
	v_cvt_pk_f32_fp8_sdwa v[174:175], v9 src0_sel:WORD_1
	v_cvt_pk_f32_fp8_e32 v[176:177], v10
	v_cvt_pk_f32_fp8_sdwa v[178:179], v10 src0_sel:WORD_1
	v_cvt_pk_f32_fp8_e32 v[180:181], v11
	v_cvt_pk_f32_fp8_sdwa v[182:183], v11 src0_sel:WORD_1
	v_pk_mul_f32 v[184:185], v[168:169], v[80:81]
	v_pk_mul_f32 v[186:187], v[170:171], v[82:83]
	v_pk_fma_f32 v[184:185], v[172:173], v[84:85], v[184:185]
	v_pk_fma_f32 v[186:187], v[174:175], v[86:87], v[186:187]
	v_pk_fma_f32 v[184:185], v[176:177], v[88:89], v[184:185]
	v_pk_fma_f32 v[186:187], v[178:179], v[90:91], v[186:187]
	v_pk_fma_f32 v[184:185], v[180:181], v[92:93], v[184:185]
	v_pk_fma_f32 v[186:187], v[182:183], v[94:95], v[186:187]
	v_pk_add_f32 v[184:185], v[184:185], v[186:187]
	v_add_f32_e32 v114, v184, v185
	s_waitcnt vmcnt(12)
	v_cvt_pk_f32_fp8_e32 v[168:169], v12
	v_cvt_pk_f32_fp8_sdwa v[170:171], v12 src0_sel:WORD_1
	v_cvt_pk_f32_fp8_e32 v[172:173], v13
	v_cvt_pk_f32_fp8_sdwa v[174:175], v13 src0_sel:WORD_1
	v_cvt_pk_f32_fp8_e32 v[176:177], v14
	v_cvt_pk_f32_fp8_sdwa v[178:179], v14 src0_sel:WORD_1
	v_cvt_pk_f32_fp8_e32 v[180:181], v15
	v_cvt_pk_f32_fp8_sdwa v[182:183], v15 src0_sel:WORD_1
	v_pk_mul_f32 v[184:185], v[168:169], v[80:81]
	v_pk_mul_f32 v[186:187], v[170:171], v[82:83]
	v_pk_fma_f32 v[184:185], v[172:173], v[84:85], v[184:185]
	v_pk_fma_f32 v[186:187], v[174:175], v[86:87], v[186:187]
	v_pk_fma_f32 v[184:185], v[176:177], v[88:89], v[184:185]
	v_pk_fma_f32 v[186:187], v[178:179], v[90:91], v[186:187]
	v_pk_fma_f32 v[184:185], v[180:181], v[92:93], v[184:185]
	v_pk_fma_f32 v[186:187], v[182:183], v[94:95], v[186:187]
	v_pk_add_f32 v[184:185], v[184:185], v[186:187]
	v_add_f32_e32 v115, v184, v185
	s_waitcnt vmcnt(11)
	v_cvt_pk_f32_fp8_e32 v[168:169], v16
	v_cvt_pk_f32_fp8_sdwa v[170:171], v16 src0_sel:WORD_1
	v_cvt_pk_f32_fp8_e32 v[172:173], v17
	v_cvt_pk_f32_fp8_sdwa v[174:175], v17 src0_sel:WORD_1
	v_cvt_pk_f32_fp8_e32 v[176:177], v18
	v_cvt_pk_f32_fp8_sdwa v[178:179], v18 src0_sel:WORD_1
	v_cvt_pk_f32_fp8_e32 v[180:181], v19
	v_cvt_pk_f32_fp8_sdwa v[182:183], v19 src0_sel:WORD_1
	v_pk_mul_f32 v[184:185], v[168:169], v[80:81]
	v_pk_mul_f32 v[186:187], v[170:171], v[82:83]
	v_pk_fma_f32 v[184:185], v[172:173], v[84:85], v[184:185]
	v_pk_fma_f32 v[186:187], v[174:175], v[86:87], v[186:187]
	v_pk_fma_f32 v[184:185], v[176:177], v[88:89], v[184:185]
	v_pk_fma_f32 v[186:187], v[178:179], v[90:91], v[186:187]
	v_pk_fma_f32 v[184:185], v[180:181], v[92:93], v[184:185]
	v_pk_fma_f32 v[186:187], v[182:183], v[94:95], v[186:187]
	v_pk_add_f32 v[184:185], v[184:185], v[186:187]
	v_add_f32_e32 v116, v184, v185
	s_waitcnt vmcnt(10)
	v_cvt_pk_f32_fp8_e32 v[168:169], v20
	v_cvt_pk_f32_fp8_sdwa v[170:171], v20 src0_sel:WORD_1
	v_cvt_pk_f32_fp8_e32 v[172:173], v21
	v_cvt_pk_f32_fp8_sdwa v[174:175], v21 src0_sel:WORD_1
	v_cvt_pk_f32_fp8_e32 v[176:177], v22
	v_cvt_pk_f32_fp8_sdwa v[178:179], v22 src0_sel:WORD_1
	v_cvt_pk_f32_fp8_e32 v[180:181], v23
	v_cvt_pk_f32_fp8_sdwa v[182:183], v23 src0_sel:WORD_1
	v_pk_mul_f32 v[184:185], v[168:169], v[80:81]
	v_pk_mul_f32 v[186:187], v[170:171], v[82:83]
	v_pk_fma_f32 v[184:185], v[172:173], v[84:85], v[184:185]
	v_pk_fma_f32 v[186:187], v[174:175], v[86:87], v[186:187]
	v_pk_fma_f32 v[184:185], v[176:177], v[88:89], v[184:185]
	v_pk_fma_f32 v[186:187], v[178:179], v[90:91], v[186:187]
	v_pk_fma_f32 v[184:185], v[180:181], v[92:93], v[184:185]
	v_pk_fma_f32 v[186:187], v[182:183], v[94:95], v[186:187]
	v_pk_add_f32 v[184:185], v[184:185], v[186:187]
	v_add_f32_e32 v117, v184, v185
	s_waitcnt vmcnt(9)
	v_cvt_pk_f32_fp8_e32 v[168:169], v24
	v_cvt_pk_f32_fp8_sdwa v[170:171], v24 src0_sel:WORD_1
	v_cvt_pk_f32_fp8_e32 v[172:173], v25
	v_cvt_pk_f32_fp8_sdwa v[174:175], v25 src0_sel:WORD_1
	v_cvt_pk_f32_fp8_e32 v[176:177], v26
	v_cvt_pk_f32_fp8_sdwa v[178:179], v26 src0_sel:WORD_1
	v_cvt_pk_f32_fp8_e32 v[180:181], v27
	v_cvt_pk_f32_fp8_sdwa v[182:183], v27 src0_sel:WORD_1
	v_pk_mul_f32 v[184:185], v[168:169], v[80:81]
	v_pk_mul_f32 v[186:187], v[170:171], v[82:83]
	v_pk_fma_f32 v[184:185], v[172:173], v[84:85], v[184:185]
	v_pk_fma_f32 v[186:187], v[174:175], v[86:87], v[186:187]
	v_pk_fma_f32 v[184:185], v[176:177], v[88:89], v[184:185]
	v_pk_fma_f32 v[186:187], v[178:179], v[90:91], v[186:187]
	v_pk_fma_f32 v[184:185], v[180:181], v[92:93], v[184:185]
	v_pk_fma_f32 v[186:187], v[182:183], v[94:95], v[186:187]
	v_pk_add_f32 v[184:185], v[184:185], v[186:187]
	v_add_f32_e32 v118, v184, v185
	s_waitcnt vmcnt(8)
	v_cvt_pk_f32_fp8_e32 v[168:169], v28
	v_cvt_pk_f32_fp8_sdwa v[170:171], v28 src0_sel:WORD_1
	v_cvt_pk_f32_fp8_e32 v[172:173], v29
	v_cvt_pk_f32_fp8_sdwa v[174:175], v29 src0_sel:WORD_1
	v_cvt_pk_f32_fp8_e32 v[176:177], v30
	v_cvt_pk_f32_fp8_sdwa v[178:179], v30 src0_sel:WORD_1
	v_cvt_pk_f32_fp8_e32 v[180:181], v31
	v_cvt_pk_f32_fp8_sdwa v[182:183], v31 src0_sel:WORD_1
	v_pk_mul_f32 v[184:185], v[168:169], v[80:81]
	v_pk_mul_f32 v[186:187], v[170:171], v[82:83]
	v_pk_fma_f32 v[184:185], v[172:173], v[84:85], v[184:185]
	v_pk_fma_f32 v[186:187], v[174:175], v[86:87], v[186:187]
	v_pk_fma_f32 v[184:185], v[176:177], v[88:89], v[184:185]
	v_pk_fma_f32 v[186:187], v[178:179], v[90:91], v[186:187]
	v_pk_fma_f32 v[184:185], v[180:181], v[92:93], v[184:185]
	v_pk_fma_f32 v[186:187], v[182:183], v[94:95], v[186:187]
	v_pk_add_f32 v[184:185], v[184:185], v[186:187]
	v_add_f32_e32 v119, v184, v185
	s_waitcnt vmcnt(7)
	v_cvt_pk_f32_fp8_e32 v[168:169], v32
	v_cvt_pk_f32_fp8_sdwa v[170:171], v32 src0_sel:WORD_1
	v_cvt_pk_f32_fp8_e32 v[172:173], v33
	v_cvt_pk_f32_fp8_sdwa v[174:175], v33 src0_sel:WORD_1
	v_cvt_pk_f32_fp8_e32 v[176:177], v34
	v_cvt_pk_f32_fp8_sdwa v[178:179], v34 src0_sel:WORD_1
	v_cvt_pk_f32_fp8_e32 v[180:181], v35
	v_cvt_pk_f32_fp8_sdwa v[182:183], v35 src0_sel:WORD_1
	v_pk_mul_f32 v[184:185], v[168:169], v[80:81]
	v_pk_mul_f32 v[186:187], v[170:171], v[82:83]
	v_pk_fma_f32 v[184:185], v[172:173], v[84:85], v[184:185]
	v_pk_fma_f32 v[186:187], v[174:175], v[86:87], v[186:187]
	v_pk_fma_f32 v[184:185], v[176:177], v[88:89], v[184:185]
	v_pk_fma_f32 v[186:187], v[178:179], v[90:91], v[186:187]
	v_pk_fma_f32 v[184:185], v[180:181], v[92:93], v[184:185]
	v_pk_fma_f32 v[186:187], v[182:183], v[94:95], v[186:187]
	v_pk_add_f32 v[184:185], v[184:185], v[186:187]
	v_add_f32_e32 v120, v184, v185
	s_waitcnt vmcnt(6)
	v_cvt_pk_f32_fp8_e32 v[168:169], v36
	v_cvt_pk_f32_fp8_sdwa v[170:171], v36 src0_sel:WORD_1
	v_cvt_pk_f32_fp8_e32 v[172:173], v37
	v_cvt_pk_f32_fp8_sdwa v[174:175], v37 src0_sel:WORD_1
	v_cvt_pk_f32_fp8_e32 v[176:177], v38
	v_cvt_pk_f32_fp8_sdwa v[178:179], v38 src0_sel:WORD_1
	v_cvt_pk_f32_fp8_e32 v[180:181], v39
	v_cvt_pk_f32_fp8_sdwa v[182:183], v39 src0_sel:WORD_1
	v_pk_mul_f32 v[184:185], v[168:169], v[80:81]
	v_pk_mul_f32 v[186:187], v[170:171], v[82:83]
	v_pk_fma_f32 v[184:185], v[172:173], v[84:85], v[184:185]
	v_pk_fma_f32 v[186:187], v[174:175], v[86:87], v[186:187]
	v_pk_fma_f32 v[184:185], v[176:177], v[88:89], v[184:185]
	v_pk_fma_f32 v[186:187], v[178:179], v[90:91], v[186:187]
	v_pk_fma_f32 v[184:185], v[180:181], v[92:93], v[184:185]
	v_pk_fma_f32 v[186:187], v[182:183], v[94:95], v[186:187]
	v_pk_add_f32 v[184:185], v[184:185], v[186:187]
	v_add_f32_e32 v121, v184, v185
	s_waitcnt vmcnt(5)
	v_cvt_pk_f32_fp8_e32 v[168:169], v40
	v_cvt_pk_f32_fp8_sdwa v[170:171], v40 src0_sel:WORD_1
	v_cvt_pk_f32_fp8_e32 v[172:173], v41
	v_cvt_pk_f32_fp8_sdwa v[174:175], v41 src0_sel:WORD_1
	v_cvt_pk_f32_fp8_e32 v[176:177], v42
	v_cvt_pk_f32_fp8_sdwa v[178:179], v42 src0_sel:WORD_1
	v_cvt_pk_f32_fp8_e32 v[180:181], v43
	v_cvt_pk_f32_fp8_sdwa v[182:183], v43 src0_sel:WORD_1
	v_pk_mul_f32 v[184:185], v[168:169], v[80:81]
	v_pk_mul_f32 v[186:187], v[170:171], v[82:83]
	v_pk_fma_f32 v[184:185], v[172:173], v[84:85], v[184:185]
	v_pk_fma_f32 v[186:187], v[174:175], v[86:87], v[186:187]
	v_pk_fma_f32 v[184:185], v[176:177], v[88:89], v[184:185]
	v_pk_fma_f32 v[186:187], v[178:179], v[90:91], v[186:187]
	v_pk_fma_f32 v[184:185], v[180:181], v[92:93], v[184:185]
	v_pk_fma_f32 v[186:187], v[182:183], v[94:95], v[186:187]
	v_pk_add_f32 v[184:185], v[184:185], v[186:187]
	v_add_f32_e32 v122, v184, v185
	s_waitcnt vmcnt(4)
	v_cvt_pk_f32_fp8_e32 v[168:169], v44
	v_cvt_pk_f32_fp8_sdwa v[170:171], v44 src0_sel:WORD_1
	v_cvt_pk_f32_fp8_e32 v[172:173], v45
	v_cvt_pk_f32_fp8_sdwa v[174:175], v45 src0_sel:WORD_1
	v_cvt_pk_f32_fp8_e32 v[176:177], v46
	v_cvt_pk_f32_fp8_sdwa v[178:179], v46 src0_sel:WORD_1
	v_cvt_pk_f32_fp8_e32 v[180:181], v47
	v_cvt_pk_f32_fp8_sdwa v[182:183], v47 src0_sel:WORD_1
	v_pk_mul_f32 v[184:185], v[168:169], v[80:81]
	v_pk_mul_f32 v[186:187], v[170:171], v[82:83]
	v_pk_fma_f32 v[184:185], v[172:173], v[84:85], v[184:185]
	v_pk_fma_f32 v[186:187], v[174:175], v[86:87], v[186:187]
	v_pk_fma_f32 v[184:185], v[176:177], v[88:89], v[184:185]
	v_pk_fma_f32 v[186:187], v[178:179], v[90:91], v[186:187]
	v_pk_fma_f32 v[184:185], v[180:181], v[92:93], v[184:185]
	v_pk_fma_f32 v[186:187], v[182:183], v[94:95], v[186:187]
	v_pk_add_f32 v[184:185], v[184:185], v[186:187]
	v_add_f32_e32 v123, v184, v185
	s_waitcnt vmcnt(3)
	v_cvt_pk_f32_fp8_e32 v[168:169], v48
	v_cvt_pk_f32_fp8_sdwa v[170:171], v48 src0_sel:WORD_1
	v_cvt_pk_f32_fp8_e32 v[172:173], v49
	v_cvt_pk_f32_fp8_sdwa v[174:175], v49 src0_sel:WORD_1
	v_cvt_pk_f32_fp8_e32 v[176:177], v50
	v_cvt_pk_f32_fp8_sdwa v[178:179], v50 src0_sel:WORD_1
	v_cvt_pk_f32_fp8_e32 v[180:181], v51
	v_cvt_pk_f32_fp8_sdwa v[182:183], v51 src0_sel:WORD_1
	v_pk_mul_f32 v[184:185], v[168:169], v[80:81]
	v_pk_mul_f32 v[186:187], v[170:171], v[82:83]
	v_pk_fma_f32 v[184:185], v[172:173], v[84:85], v[184:185]
	v_pk_fma_f32 v[186:187], v[174:175], v[86:87], v[186:187]
	v_pk_fma_f32 v[184:185], v[176:177], v[88:89], v[184:185]
	v_pk_fma_f32 v[186:187], v[178:179], v[90:91], v[186:187]
	v_pk_fma_f32 v[184:185], v[180:181], v[92:93], v[184:185]
	v_pk_fma_f32 v[186:187], v[182:183], v[94:95], v[186:187]
	v_pk_add_f32 v[184:185], v[184:185], v[186:187]
	v_add_f32_e32 v124, v184, v185
	s_waitcnt vmcnt(2)
	v_cvt_pk_f32_fp8_e32 v[168:169], v52
	v_cvt_pk_f32_fp8_sdwa v[170:171], v52 src0_sel:WORD_1
	v_cvt_pk_f32_fp8_e32 v[172:173], v53
	v_cvt_pk_f32_fp8_sdwa v[174:175], v53 src0_sel:WORD_1
	v_cvt_pk_f32_fp8_e32 v[176:177], v54
	v_cvt_pk_f32_fp8_sdwa v[178:179], v54 src0_sel:WORD_1
	v_cvt_pk_f32_fp8_e32 v[180:181], v55
	v_cvt_pk_f32_fp8_sdwa v[182:183], v55 src0_sel:WORD_1
	v_pk_mul_f32 v[184:185], v[168:169], v[80:81]
	v_pk_mul_f32 v[186:187], v[170:171], v[82:83]
	v_pk_fma_f32 v[184:185], v[172:173], v[84:85], v[184:185]
	v_pk_fma_f32 v[186:187], v[174:175], v[86:87], v[186:187]
	v_pk_fma_f32 v[184:185], v[176:177], v[88:89], v[184:185]
	v_pk_fma_f32 v[186:187], v[178:179], v[90:91], v[186:187]
	v_pk_fma_f32 v[184:185], v[180:181], v[92:93], v[184:185]
	v_pk_fma_f32 v[186:187], v[182:183], v[94:95], v[186:187]
	v_pk_add_f32 v[184:185], v[184:185], v[186:187]
	v_add_f32_e32 v125, v184, v185
	s_waitcnt vmcnt(1)
	v_cvt_pk_f32_fp8_e32 v[168:169], v56
	v_cvt_pk_f32_fp8_sdwa v[170:171], v56 src0_sel:WORD_1
	v_cvt_pk_f32_fp8_e32 v[172:173], v57
	v_cvt_pk_f32_fp8_sdwa v[174:175], v57 src0_sel:WORD_1
	v_cvt_pk_f32_fp8_e32 v[176:177], v58
	v_cvt_pk_f32_fp8_sdwa v[178:179], v58 src0_sel:WORD_1
	v_cvt_pk_f32_fp8_e32 v[180:181], v59
	v_cvt_pk_f32_fp8_sdwa v[182:183], v59 src0_sel:WORD_1
	v_pk_mul_f32 v[184:185], v[168:169], v[80:81]
	v_pk_mul_f32 v[186:187], v[170:171], v[82:83]
	v_pk_fma_f32 v[184:185], v[172:173], v[84:85], v[184:185]
	v_pk_fma_f32 v[186:187], v[174:175], v[86:87], v[186:187]
	v_pk_fma_f32 v[184:185], v[176:177], v[88:89], v[184:185]
	v_pk_fma_f32 v[186:187], v[178:179], v[90:91], v[186:187]
	v_pk_fma_f32 v[184:185], v[180:181], v[92:93], v[184:185]
	v_pk_fma_f32 v[186:187], v[182:183], v[94:95], v[186:187]
	v_pk_add_f32 v[184:185], v[184:185], v[186:187]
	v_add_f32_e32 v126, v184, v185
	s_waitcnt vmcnt(0)
	v_cvt_pk_f32_fp8_e32 v[168:169], v60
	v_cvt_pk_f32_fp8_sdwa v[170:171], v60 src0_sel:WORD_1
	v_cvt_pk_f32_fp8_e32 v[172:173], v61
	v_cvt_pk_f32_fp8_sdwa v[174:175], v61 src0_sel:WORD_1
	v_cvt_pk_f32_fp8_e32 v[176:177], v62
	v_cvt_pk_f32_fp8_sdwa v[178:179], v62 src0_sel:WORD_1
	v_cvt_pk_f32_fp8_e32 v[180:181], v63
	v_cvt_pk_f32_fp8_sdwa v[182:183], v63 src0_sel:WORD_1
	v_pk_mul_f32 v[184:185], v[168:169], v[80:81]
	v_pk_mul_f32 v[186:187], v[170:171], v[82:83]
	v_pk_fma_f32 v[184:185], v[172:173], v[84:85], v[184:185]
	v_pk_fma_f32 v[186:187], v[174:175], v[86:87], v[186:187]
	v_pk_fma_f32 v[184:185], v[176:177], v[88:89], v[184:185]
	v_pk_fma_f32 v[186:187], v[178:179], v[90:91], v[186:187]
	v_pk_fma_f32 v[184:185], v[180:181], v[92:93], v[184:185]
	v_pk_fma_f32 v[186:187], v[182:183], v[94:95], v[186:187]
	v_pk_add_f32 v[184:185], v[184:185], v[186:187]
	v_add_f32_e32 v127, v184, v185
	s_nop 1
	v_add_f32_dpp v160, v112, v112 row_half_mirror row_mask:0xf bank_mask:0x5
	v_add_f32_dpp v160, v113, v113 row_half_mirror row_mask:0xf bank_mask:0xa
	v_add_f32_dpp v161, v114, v114 row_half_mirror row_mask:0xf bank_mask:0x5
	v_add_f32_dpp v161, v115, v115 row_half_mirror row_mask:0xf bank_mask:0xa
	v_add_f32_dpp v162, v116, v116 row_half_mirror row_mask:0xf bank_mask:0x5
	v_add_f32_dpp v162, v117, v117 row_half_mirror row_mask:0xf bank_mask:0xa
	v_add_f32_dpp v163, v118, v118 row_half_mirror row_mask:0xf bank_mask:0x5
	v_add_f32_dpp v163, v119, v119 row_half_mirror row_mask:0xf bank_mask:0xa
	v_add_f32_dpp v164, v120, v120 row_half_mirror row_mask:0xf bank_mask:0x5
	v_add_f32_dpp v164, v121, v121 row_half_mirror row_mask:0xf bank_mask:0xa
	v_add_f32_dpp v165, v122, v122 row_half_mirror row_mask:0xf bank_mask:0x5
	v_add_f32_dpp v165, v123, v123 row_half_mirror row_mask:0xf bank_mask:0xa
	v_add_f32_dpp v166, v124, v124 row_half_mirror row_mask:0xf bank_mask:0x5
	v_add_f32_dpp v166, v125, v125 row_half_mirror row_mask:0xf bank_mask:0xa
	v_add_f32_dpp v167, v126, v126 row_half_mirror row_mask:0xf bank_mask:0x5
	v_add_f32_dpp v167, v127, v127 row_half_mirror row_mask:0xf bank_mask:0xa
	ds_read_b128 v[168:171], v210
	ds_read_b128 v[172:175], v210 offset:16
	s_nop 1
	v_add_f32_dpp v160, v160, v160 quad_perm:[1,0,3,2] row_mask:0xf bank_mask:0xf
	v_add_f32_dpp v161, v161, v161 quad_perm:[1,0,3,2] row_mask:0xf bank_mask:0xf
	v_add_f32_dpp v162, v162, v162 quad_perm:[1,0,3,2] row_mask:0xf bank_mask:0xf
	v_add_f32_dpp v163, v163, v163 quad_perm:[1,0,3,2] row_mask:0xf bank_mask:0xf
	v_add_f32_dpp v164, v164, v164 quad_perm:[1,0,3,2] row_mask:0xf bank_mask:0xf
	v_add_f32_dpp v165, v165, v165 quad_perm:[1,0,3,2] row_mask:0xf bank_mask:0xf
	v_add_f32_dpp v166, v166, v166 quad_perm:[1,0,3,2] row_mask:0xf bank_mask:0xf
	v_add_f32_dpp v167, v167, v167 quad_perm:[1,0,3,2] row_mask:0xf bank_mask:0xf
	s_nop 1
	v_add_f32_dpp v160, v160, v160 quad_perm:[2,3,0,1] row_mask:0xf bank_mask:0xf
	v_add_f32_dpp v161, v161, v161 quad_perm:[2,3,0,1] row_mask:0xf bank_mask:0xf
	v_add_f32_dpp v162, v162, v162 quad_perm:[2,3,0,1] row_mask:0xf bank_mask:0xf
	v_add_f32_dpp v163, v163, v163 quad_perm:[2,3,0,1] row_mask:0xf bank_mask:0xf
	v_add_f32_dpp v164, v164, v164 quad_perm:[2,3,0,1] row_mask:0xf bank_mask:0xf
	v_add_f32_dpp v165, v165, v165 quad_perm:[2,3,0,1] row_mask:0xf bank_mask:0xf
	v_add_f32_dpp v166, v166, v166 quad_perm:[2,3,0,1] row_mask:0xf bank_mask:0xf
	v_add_f32_dpp v167, v167, v167 quad_perm:[2,3,0,1] row_mask:0xf bank_mask:0xf
	s_waitcnt lgkmcnt(0)
	v_add_f32_e32 v168, v168, v160
	v_add_f32_e32 v169, v169, v161
	v_add_f32_e32 v170, v170, v162
	v_add_f32_e32 v171, v171, v163
	v_add_f32_e32 v172, v172, v164
	v_add_f32_e32 v173, v173, v165
	v_add_f32_e32 v174, v174, v166
	v_add_f32_e32 v175, v175, v167
	ds_write_b128 v210, v[168:171]
	ds_write_b128 v210, v[172:175] offset:16
	s_add_i32 s17, s17, 1
	s_cmp_lt_i32 s17, s26
	s_cbranch_scc1 .Lpb_unit
	s_add_i32 s16, s16, 1
	s_cmp_lt_i32 s16, 8
	s_cbranch_scc1 .Lpb_slice
	v_and_b32_e32 v160, 63, v218
	v_and_b32_e32 v161, 0x30, v160
	v_and_b32_e32 v162, 1, v160
	v_bfe_u32 v163, v160, 1, 3
	v_lshl_add_u32 v161, v162, 3, v161
	v_add_u32_e32 v161, v161, v163
	v_lshlrev_b32_e32 v161, 2, v161
	v_lshlrev_b32_e32 v160, 2, v160
	v_sub_u32_e32 v162, v202, v160
	v_add_u32_e32 v161, v161, v162
	v_add_u32_e32 v161, 0x2400, v161
	s_mov_b32 s17, 0
.Lpa_tok:
	s_lshl_b32 s25, s17, 9
	v_add_u32_e32 v164, s25, v161
	v_add_u32_e32 v165, s25, v202
	ds_read2st64_b32 v[166:167], v164 offset1:1
	ds_read2st64_b32 v[168:169], v165 offset0:18 offset1:19
	s_waitcnt lgkmcnt(0)
	v_mul_f32_e32 v170, 0x3f3504f3, v166
	v_cmp_nlt_f32_e64 s[0:1], |v170|, 1.0
	s_and_saveexec_b64 s[22:23], s[0:1]
	s_xor_b64 s[0:1], exec, s[22:23]
	s_cbranch_execz .Lpa_g0
	v_fma_f32 v171, |v170|, s54, v200
	v_fma_f32 v171, |v170|, v171, s55
	v_fma_f32 v171, |v170|, v171, s56
	v_fma_f32 v171, |v170|, v171, s57
	v_fma_f32 v171, |v170|, v171, s62
	v_fma_f32 v171, |v170|, v171, s63
	v_fma_f32 v171, |v170|, v171, |v170|
	v_mul_f32_e32 v176, 0xbfb8aa3b, v171
	v_fma_f32 v177, v171, s64, -v176
	v_rndne_f32_e32 v178, v176
	v_fmac_f32_e32 v177, 0xb2a5705f, v171
	v_sub_f32_e32 v176, v176, v178
	v_add_f32_e32 v176, v176, v177
	v_cvt_i32_f32_e32 v177, v178
	v_exp_f32_e32 v176, v176
	v_cmp_nlt_f32_e32 vcc, s65, v171
	v_ldexp_f32 v176, v176, v177
	s_nop 0
	v_cndmask_b32_e32 v176, 0, v176, vcc
	v_cmp_ngt_f32_e32 vcc, s66, v171
	s_nop 1
	v_cndmask_b32_e32 v171, v201, v176, vcc
	v_sub_f32_e32 v171, 1.0, v171
.Lpa_g0:
	s_andn2_saveexec_b64 s[0:1], s[0:1]
	v_mul_f32_e32 v171, v170, v170
	v_fmamk_f32 v176, v171, 0xba1345e1, v199
	v_fmaak_f32 v176, v171, v176, 0xbcdac9b8
	v_fmaak_f32 v176, v171, v176, 0x3de703be
	v_fmaak_f32 v176, v171, v176, 0xbec09330
	v_fmaak_f32 v171, v171, v176, 0x3e0375d0
	v_fma_f32 v171, |v170|, v171, |v170|
	s_or_b64 exec, exec, s[0:1]
	v_bfi_b32 v170, s67, v171, v170
	v_mul_f32_e32 v176, 0.5, v166
	v_add_f32_e32 v170, 1.0, v170
	v_mul_f32_e32 v170, v176, v170
	v_mul_f32_e32 v172, 0x3f3504f3, v167
	v_cmp_nlt_f32_e64 s[0:1], |v172|, 1.0
	s_and_saveexec_b64 s[22:23], s[0:1]
	s_xor_b64 s[0:1], exec, s[22:23]
	s_cbranch_execz .Lpa_g1
	v_fma_f32 v173, |v172|, s54, v200
	v_fma_f32 v173, |v172|, v173, s55
	v_fma_f32 v173, |v172|, v173, s56
	v_fma_f32 v173, |v172|, v173, s57
	v_fma_f32 v173, |v172|, v173, s62
	v_fma_f32 v173, |v172|, v173, s63
	v_fma_f32 v173, |v172|, v173, |v172|
	v_mul_f32_e32 v176, 0xbfb8aa3b, v173
	v_fma_f32 v177, v173, s64, -v176
	v_rndne_f32_e32 v178, v176
	v_fmac_f32_e32 v177, 0xb2a5705f, v173
	v_sub_f32_e32 v176, v176, v178
	v_add_f32_e32 v176, v176, v177
	v_cvt_i32_f32_e32 v177, v178
	v_exp_f32_e32 v176, v176
	v_cmp_nlt_f32_e32 vcc, s65, v173
	v_ldexp_f32 v176, v176, v177
	s_nop 0
	v_cndmask_b32_e32 v176, 0, v176, vcc
	v_cmp_ngt_f32_e32 vcc, s66, v173
	s_nop 1
	v_cndmask_b32_e32 v173, v201, v176, vcc
	v_sub_f32_e32 v173, 1.0, v173
.Lpa_g1:
	s_andn2_saveexec_b64 s[0:1], s[0:1]
	v_mul_f32_e32 v173, v172, v172
	v_fmamk_f32 v176, v173, 0xba1345e1, v199
	v_fmaak_f32 v176, v173, v176, 0xbcdac9b8
	v_fmaak_f32 v176, v173, v176, 0x3de703be
	v_fmaak_f32 v176, v173, v176, 0xbec09330
	v_fmaak_f32 v173, v173, v176, 0x3e0375d0
	v_fma_f32 v173, |v172|, v173, |v172|
	s_or_b64 exec, exec, s[0:1]
	v_bfi_b32 v172, s67, v173, v172
	v_mul_f32_e32 v176, 0.5, v167
	v_add_f32_e32 v172, 1.0, v172
	v_mul_f32_e32 v172, v176, v172
	v_mul_f32_e32 v170, v168, v170
	v_mul_f32_e32 v172, v169, v172
	v_mul_f32_e32 v170, 0x3d000000, v170
	v_mul_f32_e32 v172, 0x3d000000, v172
	ds_write2st64_b32 v165, v170, v172 offset0:18 offset1:19
	ds_write2st64_b32 v164, v203, v203 offset1:1
	s_add_i32 s17, s17, 1
	s_cmp_lt_i32 s17, s26
	s_cbranch_scc1 .Lpa_tok
	s_waitcnt lgkmcnt(0)
	s_mov_b32 s16, 0

.Lpc_unit:
	s_lshl_b32 s0, s17, 11
	s_add_i32 s0, s0, s27
	s_lshl_b32 s1, s16, 9
	s_lshl_b32 s24, s0, 12
	s_add_u32 s24, s24, s1
	s_add_u32 s20, s4, s24
	s_addc_u32 s21, s5, 0
	s_lshl_b32 s24, s0, 11
	s_lshr_b32 s1, s1, 1
	s_add_u32 s24, s24, s1
	s_add_u32 s36, s12, s24
	s_addc_u32 s37, s13, 0
	s_lshl_b32 s25, s16, 21
	s_add_u32 s18, s10, s25
	s_addc_u32 s19, s11, 0
	s_lshl_b32 s25, s17, 9
	v_add_u32_e32 v205, s25, v190
	v_add_u32_e32 v206, s25, v202
	ds_read_b128 v[64:67], v205
	ds_read_b128 v[68:71], v205 offset:16
	ds_read_b128 v[72:75], v205 offset:32
	ds_read_b128 v[76:79], v205 offset:48
	ds_read_b128 v[112:115], v205 offset:4608
	ds_read_b128 v[116:119], v205 offset:4624
	ds_read_b128 v[120:123], v205 offset:4640
	ds_read_b128 v[124:127], v205 offset:4656
	global_load_dwordx2 v[208:209], v211, s[20:21]
	s_waitcnt lgkmcnt(4)
	v_add_u32_e32 v64, v64, v188
	v_add_u32_e32 v65, v65, v188
	v_add_u32_e32 v66, v66, v188
	v_add_u32_e32 v67, v67, v188
	v_add_u32_e32 v68, v68, v188
	v_add_u32_e32 v69, v69, v188
	v_add_u32_e32 v70, v70, v188
	v_add_u32_e32 v71, v71, v188
	v_add_u32_e32 v72, v72, v188
	v_add_u32_e32 v73, v73, v188
	v_add_u32_e32 v74, v74, v188
	v_add_u32_e32 v75, v75, v188
	v_add_u32_e32 v76, v76, v188
	v_add_u32_e32 v77, v77, v188
	v_add_u32_e32 v78, v78, v188
	v_add_u32_e32 v79, v79, v188
	global_load_dwordx4 v[0:3], v64, s[18:19]
	global_load_dwordx4 v[4:7], v65, s[18:19]
	global_load_dwordx4 v[8:11], v66, s[18:19]
	global_load_dwordx4 v[12:15], v67, s[18:19]
	global_load_dwordx4 v[16:19], v68, s[18:19]
	global_load_dwordx4 v[20:23], v69, s[18:19]
	global_load_dwordx4 v[24:27], v70, s[18:19]
	global_load_dwordx4 v[28:31], v71, s[18:19]
	global_load_dwordx4 v[32:35], v72, s[18:19]
	global_load_dwordx4 v[36:39], v73, s[18:19]
	global_load_dwordx4 v[40:43], v74, s[18:19]
	global_load_dwordx4 v[44:47], v75, s[18:19]
	global_load_dwordx4 v[48:51], v76, s[18:19]
	global_load_dwordx4 v[52:55], v77, s[18:19]
	global_load_dwordx4 v[56:59], v78, s[18:19]
	global_load_dwordx4 v[60:63], v79, s[18:19]
	s_waitcnt lgkmcnt(0)
	s_waitcnt vmcnt(15)
	v_cvt_pk_f32_fp8_e32 v[168:169], v0
	v_cvt_pk_f32_fp8_sdwa v[170:171], v0 src0_sel:WORD_1
	v_cvt_pk_f32_fp8_e32 v[172:173], v1
	v_cvt_pk_f32_fp8_sdwa v[174:175], v1 src0_sel:WORD_1
	v_cvt_pk_f32_fp8_e32 v[176:177], v2
	v_cvt_pk_f32_fp8_sdwa v[178:179], v2 src0_sel:WORD_1
	v_cvt_pk_f32_fp8_e32 v[180:181], v3
	v_cvt_pk_f32_fp8_sdwa v[182:183], v3 src0_sel:WORD_1
	v_pk_mul_f32 v[144:145], v[168:169], v[112:113] op_sel_hi:[1,0]
	v_pk_mul_f32 v[146:147], v[170:171], v[112:113] op_sel_hi:[1,0]
	v_pk_mul_f32 v[148:149], v[172:173], v[112:113] op_sel_hi:[1,0]
	v_pk_mul_f32 v[150:151], v[174:175], v[112:113] op_sel_hi:[1,0]
	v_pk_mul_f32 v[152:153], v[176:177], v[112:113] op_sel_hi:[1,0]
	v_pk_mul_f32 v[154:155], v[178:179], v[112:113] op_sel_hi:[1,0]
	v_pk_mul_f32 v[156:157], v[180:181], v[112:113] op_sel_hi:[1,0]
	v_pk_mul_f32 v[158:159], v[182:183], v[112:113] op_sel_hi:[1,0]
	s_waitcnt vmcnt(14)
	v_cvt_pk_f32_fp8_e32 v[168:169], v4
	v_cvt_pk_f32_fp8_sdwa v[170:171], v4 src0_sel:WORD_1
	v_cvt_pk_f32_fp8_e32 v[172:173], v5
	v_cvt_pk_f32_fp8_sdwa v[174:175], v5 src0_sel:WORD_1
	v_cvt_pk_f32_fp8_e32 v[176:177], v6
	v_cvt_pk_f32_fp8_sdwa v[178:179], v6 src0_sel:WORD_1
	v_cvt_pk_f32_fp8_e32 v[180:181], v7
	v_cvt_pk_f32_fp8_sdwa v[182:183], v7 src0_sel:WORD_1
	v_pk_fma_f32 v[144:145], v[168:169], v[112:113], v[144:145] op_sel:[0,1,0] op_sel_hi:[1,1,1]
	v_pk_fma_f32 v[146:147], v[170:171], v[112:113], v[146:147] op_sel:[0,1,0] op_sel_hi:[1,1,1]
	v_pk_fma_f32 v[148:149], v[172:173], v[112:113], v[148:149] op_sel:[0,1,0] op_sel_hi:[1,1,1]
	v_pk_fma_f32 v[150:151], v[174:175], v[112:113], v[150:151] op_sel:[0,1,0] op_sel_hi:[1,1,1]
	v_pk_fma_f32 v[152:153], v[176:177], v[112:113], v[152:153] op_sel:[0,1,0] op_sel_hi:[1,1,1]
	v_pk_fma_f32 v[154:155], v[178:179], v[112:113], v[154:155] op_sel:[0,1,0] op_sel_hi:[1,1,1]
	v_pk_fma_f32 v[156:157], v[180:181], v[112:113], v[156:157] op_sel:[0,1,0] op_sel_hi:[1,1,1]
	v_pk_fma_f32 v[158:159], v[182:183], v[112:113], v[158:159] op_sel:[0,1,0] op_sel_hi:[1,1,1]
	s_waitcnt vmcnt(13)
	v_cvt_pk_f32_fp8_e32 v[168:169], v8
	v_cvt_pk_f32_fp8_sdwa v[170:171], v8 src0_sel:WORD_1
	v_cvt_pk_f32_fp8_e32 v[172:173], v9
	v_cvt_pk_f32_fp8_sdwa v[174:175], v9 src0_sel:WORD_1
	v_cvt_pk_f32_fp8_e32 v[176:177], v10
	v_cvt_pk_f32_fp8_sdwa v[178:179], v10 src0_sel:WORD_1
	v_cvt_pk_f32_fp8_e32 v[180:181], v11
	v_cvt_pk_f32_fp8_sdwa v[182:183], v11 src0_sel:WORD_1
	v_pk_fma_f32 v[144:145], v[168:169], v[114:115], v[144:145] op_sel_hi:[1,0,1]
	v_pk_fma_f32 v[146:147], v[170:171], v[114:115], v[146:147] op_sel_hi:[1,0,1]
	v_pk_fma_f32 v[148:149], v[172:173], v[114:115], v[148:149] op_sel_hi:[1,0,1]
	v_pk_fma_f32 v[150:151], v[174:175], v[114:115], v[150:151] op_sel_hi:[1,0,1]
	v_pk_fma_f32 v[152:153], v[176:177], v[114:115], v[152:153] op_sel_hi:[1,0,1]
	v_pk_fma_f32 v[154:155], v[178:179], v[114:115], v[154:155] op_sel_hi:[1,0,1]
	v_pk_fma_f32 v[156:157], v[180:181], v[114:115], v[156:157] op_sel_hi:[1,0,1]
	v_pk_fma_f32 v[158:159], v[182:183], v[114:115], v[158:159] op_sel_hi:[1,0,1]
	s_waitcnt vmcnt(12)
	v_cvt_pk_f32_fp8_e32 v[168:169], v12
	v_cvt_pk_f32_fp8_sdwa v[170:171], v12 src0_sel:WORD_1
	v_cvt_pk_f32_fp8_e32 v[172:173], v13
	v_cvt_pk_f32_fp8_sdwa v[174:175], v13 src0_sel:WORD_1
	v_cvt_pk_f32_fp8_e32 v[176:177], v14
	v_cvt_pk_f32_fp8_sdwa v[178:179], v14 src0_sel:WORD_1
	v_cvt_pk_f32_fp8_e32 v[180:181], v15
	v_cvt_pk_f32_fp8_sdwa v[182:183], v15 src0_sel:WORD_1
	v_pk_fma_f32 v[144:145], v[168:169], v[114:115], v[144:145] op_sel:[0,1,0] op_sel_hi:[1,1,1]
	v_pk_fma_f32 v[146:147], v[170:171], v[114:115], v[146:147] op_sel:[0,1,0] op_sel_hi:[1,1,1]
	v_pk_fma_f32 v[148:149], v[172:173], v[114:115], v[148:149] op_sel:[0,1,0] op_sel_hi:[1,1,1]
	v_pk_fma_f32 v[150:151], v[174:175], v[114:115], v[150:151] op_sel:[0,1,0] op_sel_hi:[1,1,1]
	v_pk_fma_f32 v[152:153], v[176:177], v[114:115], v[152:153] op_sel:[0,1,0] op_sel_hi:[1,1,1]
	v_pk_fma_f32 v[154:155], v[178:179], v[114:115], v[154:155] op_sel:[0,1,0] op_sel_hi:[1,1,1]
	v_pk_fma_f32 v[156:157], v[180:181], v[114:115], v[156:157] op_sel:[0,1,0] op_sel_hi:[1,1,1]
	v_pk_fma_f32 v[158:159], v[182:183], v[114:115], v[158:159] op_sel:[0,1,0] op_sel_hi:[1,1,1]
	s_waitcnt vmcnt(11)
	v_cvt_pk_f32_fp8_e32 v[168:169], v16
	v_cvt_pk_f32_fp8_sdwa v[170:171], v16 src0_sel:WORD_1
	v_cvt_pk_f32_fp8_e32 v[172:173], v17
	v_cvt_pk_f32_fp8_sdwa v[174:175], v17 src0_sel:WORD_1
	v_cvt_pk_f32_fp8_e32 v[176:177], v18
	v_cvt_pk_f32_fp8_sdwa v[178:179], v18 src0_sel:WORD_1
	v_cvt_pk_f32_fp8_e32 v[180:181], v19
	v_cvt_pk_f32_fp8_sdwa v[182:183], v19 src0_sel:WORD_1
	v_pk_fma_f32 v[144:145], v[168:169], v[116:117], v[144:145] op_sel_hi:[1,0,1]
	v_pk_fma_f32 v[146:147], v[170:171], v[116:117], v[146:147] op_sel_hi:[1,0,1]
	v_pk_fma_f32 v[148:149], v[172:173], v[116:117], v[148:149] op_sel_hi:[1,0,1]
	v_pk_fma_f32 v[150:151], v[174:175], v[116:117], v[150:151] op_sel_hi:[1,0,1]
	v_pk_fma_f32 v[152:153], v[176:177], v[116:117], v[152:153] op_sel_hi:[1,0,1]
	v_pk_fma_f32 v[154:155], v[178:179], v[116:117], v[154:155] op_sel_hi:[1,0,1]
	v_pk_fma_f32 v[156:157], v[180:181], v[116:117], v[156:157] op_sel_hi:[1,0,1]
	v_pk_fma_f32 v[158:159], v[182:183], v[116:117], v[158:159] op_sel_hi:[1,0,1]
	s_waitcnt vmcnt(10)
	v_cvt_pk_f32_fp8_e32 v[168:169], v20
	v_cvt_pk_f32_fp8_sdwa v[170:171], v20 src0_sel:WORD_1
	v_cvt_pk_f32_fp8_e32 v[172:173], v21
	v_cvt_pk_f32_fp8_sdwa v[174:175], v21 src0_sel:WORD_1
	v_cvt_pk_f32_fp8_e32 v[176:177], v22
	v_cvt_pk_f32_fp8_sdwa v[178:179], v22 src0_sel:WORD_1
	v_cvt_pk_f32_fp8_e32 v[180:181], v23
	v_cvt_pk_f32_fp8_sdwa v[182:183], v23 src0_sel:WORD_1
	v_pk_fma_f32 v[144:145], v[168:169], v[116:117], v[144:145] op_sel:[0,1,0] op_sel_hi:[1,1,1]
	v_pk_fma_f32 v[146:147], v[170:171], v[116:117], v[146:147] op_sel:[0,1,0] op_sel_hi:[1,1,1]
	v_pk_fma_f32 v[148:149], v[172:173], v[116:117], v[148:149] op_sel:[0,1,0] op_sel_hi:[1,1,1]
	v_pk_fma_f32 v[150:151], v[174:175], v[116:117], v[150:151] op_sel:[0,1,0] op_sel_hi:[1,1,1]
	v_pk_fma_f32 v[152:153], v[176:177], v[116:117], v[152:153] op_sel:[0,1,0] op_sel_hi:[1,1,1]
	v_pk_fma_f32 v[154:155], v[178:179], v[116:117], v[154:155] op_sel:[0,1,0] op_sel_hi:[1,1,1]
	v_pk_fma_f32 v[156:157], v[180:181], v[116:117], v[156:157] op_sel:[0,1,0] op_sel_hi:[1,1,1]
	v_pk_fma_f32 v[158:159], v[182:183], v[116:117], v[158:159] op_sel:[0,1,0] op_sel_hi:[1,1,1]
	s_waitcnt vmcnt(9)
	v_cvt_pk_f32_fp8_e32 v[168:169], v24
	v_cvt_pk_f32_fp8_sdwa v[170:171], v24 src0_sel:WORD_1
	v_cvt_pk_f32_fp8_e32 v[172:173], v25
	v_cvt_pk_f32_fp8_sdwa v[174:175], v25 src0_sel:WORD_1
	v_cvt_pk_f32_fp8_e32 v[176:177], v26
	v_cvt_pk_f32_fp8_sdwa v[178:179], v26 src0_sel:WORD_1
	v_cvt_pk_f32_fp8_e32 v[180:181], v27
	v_cvt_pk_f32_fp8_sdwa v[182:183], v27 src0_sel:WORD_1
	v_pk_fma_f32 v[144:145], v[168:169], v[118:119], v[144:145] op_sel_hi:[1,0,1]
	v_pk_fma_f32 v[146:147], v[170:171], v[118:119], v[146:147] op_sel_hi:[1,0,1]
	v_pk_fma_f32 v[148:149], v[172:173], v[118:119], v[148:149] op_sel_hi:[1,0,1]
	v_pk_fma_f32 v[150:151], v[174:175], v[118:119], v[150:151] op_sel_hi:[1,0,1]
	v_pk_fma_f32 v[152:153], v[176:177], v[118:119], v[152:153] op_sel_hi:[1,0,1]
	v_pk_fma_f32 v[154:155], v[178:179], v[118:119], v[154:155] op_sel_hi:[1,0,1]
	v_pk_fma_f32 v[156:157], v[180:181], v[118:119], v[156:157] op_sel_hi:[1,0,1]
	v_pk_fma_f32 v[158:159], v[182:183], v[118:119], v[158:159] op_sel_hi:[1,0,1]
	s_waitcnt vmcnt(8)
	v_cvt_pk_f32_fp8_e32 v[168:169], v28
	v_cvt_pk_f32_fp8_sdwa v[170:171], v28 src0_sel:WORD_1
	v_cvt_pk_f32_fp8_e32 v[172:173], v29
	v_cvt_pk_f32_fp8_sdwa v[174:175], v29 src0_sel:WORD_1
	v_cvt_pk_f32_fp8_e32 v[176:177], v30
	v_cvt_pk_f32_fp8_sdwa v[178:179], v30 src0_sel:WORD_1
	v_cvt_pk_f32_fp8_e32 v[180:181], v31
	v_cvt_pk_f32_fp8_sdwa v[182:183], v31 src0_sel:WORD_1
	v_pk_fma_f32 v[144:145], v[168:169], v[118:119], v[144:145] op_sel:[0,1,0] op_sel_hi:[1,1,1]
	v_pk_fma_f32 v[146:147], v[170:171], v[118:119], v[146:147] op_sel:[0,1,0] op_sel_hi:[1,1,1]
	v_pk_fma_f32 v[148:149], v[172:173], v[118:119], v[148:149] op_sel:[0,1,0] op_sel_hi:[1,1,1]
	v_pk_fma_f32 v[150:151], v[174:175], v[118:119], v[150:151] op_sel:[0,1,0] op_sel_hi:[1,1,1]
	v_pk_fma_f32 v[152:153], v[176:177], v[118:119], v[152:153] op_sel:[0,1,0] op_sel_hi:[1,1,1]
	v_pk_fma_f32 v[154:155], v[178:179], v[118:119], v[154:155] op_sel:[0,1,0] op_sel_hi:[1,1,1]
	v_pk_fma_f32 v[156:157], v[180:181], v[118:119], v[156:157] op_sel:[0,1,0] op_sel_hi:[1,1,1]
	v_pk_fma_f32 v[158:159], v[182:183], v[118:119], v[158:159] op_sel:[0,1,0] op_sel_hi:[1,1,1]
	s_waitcnt vmcnt(7)
	v_cvt_pk_f32_fp8_e32 v[168:169], v32
	v_cvt_pk_f32_fp8_sdwa v[170:171], v32 src0_sel:WORD_1
	v_cvt_pk_f32_fp8_e32 v[172:173], v33
	v_cvt_pk_f32_fp8_sdwa v[174:175], v33 src0_sel:WORD_1
	v_cvt_pk_f32_fp8_e32 v[176:177], v34
	v_cvt_pk_f32_fp8_sdwa v[178:179], v34 src0_sel:WORD_1
	v_cvt_pk_f32_fp8_e32 v[180:181], v35
	v_cvt_pk_f32_fp8_sdwa v[182:183], v35 src0_sel:WORD_1
	v_pk_fma_f32 v[144:145], v[168:169], v[120:121], v[144:145] op_sel_hi:[1,0,1]
	v_pk_fma_f32 v[146:147], v[170:171], v[120:121], v[146:147] op_sel_hi:[1,0,1]
	v_pk_fma_f32 v[148:149], v[172:173], v[120:121], v[148:149] op_sel_hi:[1,0,1]
	v_pk_fma_f32 v[150:151], v[174:175], v[120:121], v[150:151] op_sel_hi:[1,0,1]
	v_pk_fma_f32 v[152:153], v[176:177], v[120:121], v[152:153] op_sel_hi:[1,0,1]
	v_pk_fma_f32 v[154:155], v[178:179], v[120:121], v[154:155] op_sel_hi:[1,0,1]
	v_pk_fma_f32 v[156:157], v[180:181], v[120:121], v[156:157] op_sel_hi:[1,0,1]
	v_pk_fma_f32 v[158:159], v[182:183], v[120:121], v[158:159] op_sel_hi:[1,0,1]
	s_waitcnt vmcnt(6)
	v_cvt_pk_f32_fp8_e32 v[168:169], v36
	v_cvt_pk_f32_fp8_sdwa v[170:171], v36 src0_sel:WORD_1
	v_cvt_pk_f32_fp8_e32 v[172:173], v37
	v_cvt_pk_f32_fp8_sdwa v[174:175], v37 src0_sel:WORD_1
	v_cvt_pk_f32_fp8_e32 v[176:177], v38
	v_cvt_pk_f32_fp8_sdwa v[178:179], v38 src0_sel:WORD_1
	v_cvt_pk_f32_fp8_e32 v[180:181], v39
	v_cvt_pk_f32_fp8_sdwa v[182:183], v39 src0_sel:WORD_1
	v_pk_fma_f32 v[144:145], v[168:169], v[120:121], v[144:145] op_sel:[0,1,0] op_sel_hi:[1,1,1]
	v_pk_fma_f32 v[146:147], v[170:171], v[120:121], v[146:147] op_sel:[0,1,0] op_sel_hi:[1,1,1]
	v_pk_fma_f32 v[148:149], v[172:173], v[120:121], v[148:149] op_sel:[0,1,0] op_sel_hi:[1,1,1]
	v_pk_fma_f32 v[150:151], v[174:175], v[120:121], v[150:151] op_sel:[0,1,0] op_sel_hi:[1,1,1]
	v_pk_fma_f32 v[152:153], v[176:177], v[120:121], v[152:153] op_sel:[0,1,0] op_sel_hi:[1,1,1]
	v_pk_fma_f32 v[154:155], v[178:179], v[120:121], v[154:155] op_sel:[0,1,0] op_sel_hi:[1,1,1]
	v_pk_fma_f32 v[156:157], v[180:181], v[120:121], v[156:157] op_sel:[0,1,0] op_sel_hi:[1,1,1]
	v_pk_fma_f32 v[158:159], v[182:183], v[120:121], v[158:159] op_sel:[0,1,0] op_sel_hi:[1,1,1]
	s_waitcnt vmcnt(5)
	v_cvt_pk_f32_fp8_e32 v[168:169], v40
	v_cvt_pk_f32_fp8_sdwa v[170:171], v40 src0_sel:WORD_1
	v_cvt_pk_f32_fp8_e32 v[172:173], v41
	v_cvt_pk_f32_fp8_sdwa v[174:175], v41 src0_sel:WORD_1
	v_cvt_pk_f32_fp8_e32 v[176:177], v42
	v_cvt_pk_f32_fp8_sdwa v[178:179], v42 src0_sel:WORD_1
	v_cvt_pk_f32_fp8_e32 v[180:181], v43
	v_cvt_pk_f32_fp8_sdwa v[182:183], v43 src0_sel:WORD_1
	v_pk_fma_f32 v[144:145], v[168:169], v[122:123], v[144:145] op_sel_hi:[1,0,1]
	v_pk_fma_f32 v[146:147], v[170:171], v[122:123], v[146:147] op_sel_hi:[1,0,1]
	v_pk_fma_f32 v[148:149], v[172:173], v[122:123], v[148:149] op_sel_hi:[1,0,1]
	v_pk_fma_f32 v[150:151], v[174:175], v[122:123], v[150:151] op_sel_hi:[1,0,1]
	v_pk_fma_f32 v[152:153], v[176:177], v[122:123], v[152:153] op_sel_hi:[1,0,1]
	v_pk_fma_f32 v[154:155], v[178:179], v[122:123], v[154:155] op_sel_hi:[1,0,1]
	v_pk_fma_f32 v[156:157], v[180:181], v[122:123], v[156:157] op_sel_hi:[1,0,1]
	v_pk_fma_f32 v[158:159], v[182:183], v[122:123], v[158:159] op_sel_hi:[1,0,1]
	s_waitcnt vmcnt(4)
	v_cvt_pk_f32_fp8_e32 v[168:169], v44
	v_cvt_pk_f32_fp8_sdwa v[170:171], v44 src0_sel:WORD_1
	v_cvt_pk_f32_fp8_e32 v[172:173], v45
	v_cvt_pk_f32_fp8_sdwa v[174:175], v45 src0_sel:WORD_1
	v_cvt_pk_f32_fp8_e32 v[176:177], v46
	v_cvt_pk_f32_fp8_sdwa v[178:179], v46 src0_sel:WORD_1
	v_cvt_pk_f32_fp8_e32 v[180:181], v47
	v_cvt_pk_f32_fp8_sdwa v[182:183], v47 src0_sel:WORD_1
	v_pk_fma_f32 v[144:145], v[168:169], v[122:123], v[144:145] op_sel:[0,1,0] op_sel_hi:[1,1,1]
	v_pk_fma_f32 v[146:147], v[170:171], v[122:123], v[146:147] op_sel:[0,1,0] op_sel_hi:[1,1,1]
	v_pk_fma_f32 v[148:149], v[172:173], v[122:123], v[148:149] op_sel:[0,1,0] op_sel_hi:[1,1,1]
	v_pk_fma_f32 v[150:151], v[174:175], v[122:123], v[150:151] op_sel:[0,1,0] op_sel_hi:[1,1,1]
	v_pk_fma_f32 v[152:153], v[176:177], v[122:123], v[152:153] op_sel:[0,1,0] op_sel_hi:[1,1,1]
	v_pk_fma_f32 v[154:155], v[178:179], v[122:123], v[154:155] op_sel:[0,1,0] op_sel_hi:[1,1,1]
	v_pk_fma_f32 v[156:157], v[180:181], v[122:123], v[156:157] op_sel:[0,1,0] op_sel_hi:[1,1,1]
	v_pk_fma_f32 v[158:159], v[182:183], v[122:123], v[158:159] op_sel:[0,1,0] op_sel_hi:[1,1,1]
	s_waitcnt vmcnt(3)
	v_cvt_pk_f32_fp8_e32 v[168:169], v48
	v_cvt_pk_f32_fp8_sdwa v[170:171], v48 src0_sel:WORD_1
	v_cvt_pk_f32_fp8_e32 v[172:173], v49
	v_cvt_pk_f32_fp8_sdwa v[174:175], v49 src0_sel:WORD_1
	v_cvt_pk_f32_fp8_e32 v[176:177], v50
	v_cvt_pk_f32_fp8_sdwa v[178:179], v50 src0_sel:WORD_1
	v_cvt_pk_f32_fp8_e32 v[180:181], v51
	v_cvt_pk_f32_fp8_sdwa v[182:183], v51 src0_sel:WORD_1
	v_pk_fma_f32 v[144:145], v[168:169], v[124:125], v[144:145] op_sel_hi:[1,0,1]
	v_pk_fma_f32 v[146:147], v[170:171], v[124:125], v[146:147] op_sel_hi:[1,0,1]
	v_pk_fma_f32 v[148:149], v[172:173], v[124:125], v[148:149] op_sel_hi:[1,0,1]
	v_pk_fma_f32 v[150:151], v[174:175], v[124:125], v[150:151] op_sel_hi:[1,0,1]
	v_pk_fma_f32 v[152:153], v[176:177], v[124:125], v[152:153] op_sel_hi:[1,0,1]
	v_pk_fma_f32 v[154:155], v[178:179], v[124:125], v[154:155] op_sel_hi:[1,0,1]
	v_pk_fma_f32 v[156:157], v[180:181], v[124:125], v[156:157] op_sel_hi:[1,0,1]
	v_pk_fma_f32 v[158:159], v[182:183], v[124:125], v[158:159] op_sel_hi:[1,0,1]
	s_waitcnt vmcnt(2)
	v_cvt_pk_f32_fp8_e32 v[168:169], v52
	v_cvt_pk_f32_fp8_sdwa v[170:171], v52 src0_sel:WORD_1
	v_cvt_pk_f32_fp8_e32 v[172:173], v53
	v_cvt_pk_f32_fp8_sdwa v[174:175], v53 src0_sel:WORD_1
	v_cvt_pk_f32_fp8_e32 v[176:177], v54
	v_cvt_pk_f32_fp8_sdwa v[178:179], v54 src0_sel:WORD_1
	v_cvt_pk_f32_fp8_e32 v[180:181], v55
	v_cvt_pk_f32_fp8_sdwa v[182:183], v55 src0_sel:WORD_1
	v_pk_fma_f32 v[144:145], v[168:169], v[124:125], v[144:145] op_sel:[0,1,0] op_sel_hi:[1,1,1]
	v_pk_fma_f32 v[146:147], v[170:171], v[124:125], v[146:147] op_sel:[0,1,0] op_sel_hi:[1,1,1]
	v_pk_fma_f32 v[148:149], v[172:173], v[124:125], v[148:149] op_sel:[0,1,0] op_sel_hi:[1,1,1]
	v_pk_fma_f32 v[150:151], v[174:175], v[124:125], v[150:151] op_sel:[0,1,0] op_sel_hi:[1,1,1]
	v_pk_fma_f32 v[152:153], v[176:177], v[124:125], v[152:153] op_sel:[0,1,0] op_sel_hi:[1,1,1]
	v_pk_fma_f32 v[154:155], v[178:179], v[124:125], v[154:155] op_sel:[0,1,0] op_sel_hi:[1,1,1]
	v_pk_fma_f32 v[156:157], v[180:181], v[124:125], v[156:157] op_sel:[0,1,0] op_sel_hi:[1,1,1]
	v_pk_fma_f32 v[158:159], v[182:183], v[124:125], v[158:159] op_sel:[0,1,0] op_sel_hi:[1,1,1]
	s_waitcnt vmcnt(1)
	v_cvt_pk_f32_fp8_e32 v[168:169], v56
	v_cvt_pk_f32_fp8_sdwa v[170:171], v56 src0_sel:WORD_1
	v_cvt_pk_f32_fp8_e32 v[172:173], v57
	v_cvt_pk_f32_fp8_sdwa v[174:175], v57 src0_sel:WORD_1
	v_cvt_pk_f32_fp8_e32 v[176:177], v58
	v_cvt_pk_f32_fp8_sdwa v[178:179], v58 src0_sel:WORD_1
	v_cvt_pk_f32_fp8_e32 v[180:181], v59
	v_cvt_pk_f32_fp8_sdwa v[182:183], v59 src0_sel:WORD_1
	v_pk_fma_f32 v[144:145], v[168:169], v[126:127], v[144:145] op_sel_hi:[1,0,1]
	v_pk_fma_f32 v[146:147], v[170:171], v[126:127], v[146:147] op_sel_hi:[1,0,1]
	v_pk_fma_f32 v[148:149], v[172:173], v[126:127], v[148:149] op_sel_hi:[1,0,1]
	v_pk_fma_f32 v[150:151], v[174:175], v[126:127], v[150:151] op_sel_hi:[1,0,1]
	v_pk_fma_f32 v[152:153], v[176:177], v[126:127], v[152:153] op_sel_hi:[1,0,1]
	v_pk_fma_f32 v[154:155], v[178:179], v[126:127], v[154:155] op_sel_hi:[1,0,1]
	v_pk_fma_f32 v[156:157], v[180:181], v[126:127], v[156:157] op_sel_hi:[1,0,1]
	v_pk_fma_f32 v[158:159], v[182:183], v[126:127], v[158:159] op_sel_hi:[1,0,1]
	s_waitcnt vmcnt(0)
	v_cvt_pk_f32_fp8_e32 v[168:169], v60
	v_cvt_pk_f32_fp8_sdwa v[170:171], v60 src0_sel:WORD_1
	v_cvt_pk_f32_fp8_e32 v[172:173], v61
	v_cvt_pk_f32_fp8_sdwa v[174:175], v61 src0_sel:WORD_1
	v_cvt_pk_f32_fp8_e32 v[176:177], v62
	v_cvt_pk_f32_fp8_sdwa v[178:179], v62 src0_sel:WORD_1
	v_cvt_pk_f32_fp8_e32 v[180:181], v63
	v_cvt_pk_f32_fp8_sdwa v[182:183], v63 src0_sel:WORD_1
	v_pk_fma_f32 v[144:145], v[168:169], v[126:127], v[144:145] op_sel:[0,1,0] op_sel_hi:[1,1,1]
	v_pk_fma_f32 v[146:147], v[170:171], v[126:127], v[146:147] op_sel:[0,1,0] op_sel_hi:[1,1,1]
	v_pk_fma_f32 v[148:149], v[172:173], v[126:127], v[148:149] op_sel:[0,1,0] op_sel_hi:[1,1,1]
	v_pk_fma_f32 v[150:151], v[174:175], v[126:127], v[150:151] op_sel:[0,1,0] op_sel_hi:[1,1,1]
	v_pk_fma_f32 v[152:153], v[176:177], v[126:127], v[152:153] op_sel:[0,1,0] op_sel_hi:[1,1,1]
	v_pk_fma_f32 v[154:155], v[178:179], v[126:127], v[154:155] op_sel:[0,1,0] op_sel_hi:[1,1,1]
	v_pk_fma_f32 v[156:157], v[180:181], v[126:127], v[156:157] op_sel:[0,1,0] op_sel_hi:[1,1,1]
	v_pk_fma_f32 v[158:159], v[182:183], v[126:127], v[158:159] op_sel:[0,1,0] op_sel_hi:[1,1,1]
	s_nop 1
	v_permlane32_swap_b32_e32 v144, v152
	v_permlane32_swap_b32_e32 v145, v153
	v_permlane32_swap_b32_e32 v146, v154
	v_permlane32_swap_b32_e32 v147, v155
	v_permlane32_swap_b32_e32 v148, v156
	v_permlane32_swap_b32_e32 v149, v157
	v_permlane32_swap_b32_e32 v150, v158
	v_permlane32_swap_b32_e32 v151, v159
	v_add_f32_e32 v144, v144, v152
	v_add_f32_e32 v145, v145, v153
	v_add_f32_e32 v146, v146, v154
	v_add_f32_e32 v147, v147, v155
	v_add_f32_e32 v148, v148, v156
	v_add_f32_e32 v149, v149, v157
	v_add_f32_e32 v150, v150, v158
	v_add_f32_e32 v151, v151, v159
	v_cndmask_b32_e64 v152, v148, v144, s[38:39]
	v_cndmask_b32_e64 v156, v144, v148, s[38:39]
	v_cndmask_b32_e64 v153, v149, v145, s[38:39]
	v_cndmask_b32_e64 v157, v145, v149, s[38:39]
	v_cndmask_b32_e64 v154, v150, v146, s[38:39]
	v_cndmask_b32_e64 v158, v146, v150, s[38:39]
	v_cndmask_b32_e64 v155, v151, v147, s[38:39]
	v_cndmask_b32_e64 v159, v147, v151, s[38:39]
	ds_bpermute_b32 v152, v138, v152
	ds_bpermute_b32 v153, v138, v153
	ds_bpermute_b32 v154, v138, v154
	ds_bpermute_b32 v155, v138, v155
	s_waitcnt lgkmcnt(0)
	v_add_f32_e32 v144, v156, v152
	v_add_f32_e32 v145, v157, v153
	v_add_f32_e32 v146, v158, v154
	v_add_f32_e32 v147, v159, v155
	s_nop 1
	v_add_f32_dpp v148, v144, v144 row_ror:8 row_mask:0xf bank_mask:0x3
	v_add_f32_dpp v149, v145, v145 row_ror:8 row_mask:0xf bank_mask:0x3
	v_add_f32_dpp v148, v146, v146 row_ror:8 row_mask:0xf bank_mask:0xc
	v_add_f32_dpp v149, v147, v147 row_ror:8 row_mask:0xf bank_mask:0xc
	s_waitcnt vmcnt(0)
	v_add_f32_e32 v208, v208, v148
	v_add_f32_e32 v209, v209, v149
	global_store_dwordx2 v211, v[208:209], s[20:21]
	v_cvt_pk_bf16_f32 v212, v208, v209
	v_mul_f32_e32 v193, v208, v208
	v_fmac_f32_e32 v193, v209, v209
	global_store_dword v213, v212, s[36:37]
	ds_add_f32 v206, v193 offset:9216
	s_add_i32 s17, s17, 1
	s_cmp_lt_i32 s17, s26
	s_cbranch_scc1 .Lpc_unit
	s_add_i32 s16, s16, 1
	s_cmp_lt_i32 s16, 8
	s_cbranch_scc1 .Lpc_slice
	s_mov_b32 s17, 0
.Lpd_tok:
	s_lshl_b32 s25, s17, 9
	v_add_u32_e32 v206, s25, v202
	ds_read_b32 v16, v206 offset:9216
	s_lshl_b32 s0, s17, 11
	s_add_i32 s0, s0, s27
	s_lshl_b32 s0, s0, 2
	s_add_u32 s20, s14, s0
	s_addc_u32 s21, s15, 0
	s_waitcnt lgkmcnt(0)
	ds_bpermute_b32 v17, v137, v16
	s_waitcnt lgkmcnt(0)
	v_add_f32_e32 v16, v16, v17
	ds_bpermute_b32 v17, v138, v16
	s_waitcnt lgkmcnt(0)
	v_add_f32_e32 v16, v16, v17
	ds_bpermute_b32 v17, v139, v16
	s_waitcnt lgkmcnt(0)
	v_add_f32_e32 v16, v16, v17
	ds_bpermute_b32 v17, v140, v16
	s_waitcnt lgkmcnt(0)
	v_add_f32_e32 v16, v16, v17
	ds_bpermute_b32 v17, v141, v16
	s_waitcnt lgkmcnt(0)
	v_add_f32_e32 v16, v16, v17
	ds_bpermute_b32 v17, v142, v16
	s_waitcnt lgkmcnt(0)
	v_add_f32_e32 v16, v16, v17
	v_fmamk_f32 v16, v16, 0x3a800000, v198
	v_mul_f32_e32 v17, 0x4b800000, v16
	v_cmp_gt_f32_e32 vcc, s35, v16
	s_nop 1
	v_cndmask_b32_e32 v16, v16, v17, vcc
	v_rsq_f32_e32 v16, v16
	s_nop 0
	v_mul_f32_e32 v17, 0x45800000, v16
	v_cndmask_b32_e32 v18, v16, v17, vcc
	global_store_dword v203, v18, s[20:21]
	s_add_i32 s17, s17, 1
	s_cmp_lt_i32 s17, s26
	s_cbranch_scc1 .Lpd_tok
